# p_mod prologue matvec: serialized load-wait-fma k-loop replaced by a rolling 16-deep load window (same fma order, bit-identical)
# speedup vs baseline: 1.0074x; 1.0060x over previous
;     DI const float* inp(int i) const { return as_global(P.in[i]); }
; DI void p_mod(const Frame& F) {
;     ...
;         const float* w = F.inp(4) + (size_t)l * 2048 * 12288 + colb + c4 * 4;
;         f32x4 a0 = {0.f, 0.f, 0.f, 0.f}, a1 = a0, a2 = a0, a3 = a0, a4 = a0;
; #pragma unroll 16
;         for (int k = kg * 128; k < kg * 128 + 128; ++k) { const f32x4 wv = __builtin_nontemporal_load((const f32x4*)(w + (size_t)k * 12288));
;             a0 += sv[k] * wv; a1 += sv[2048 + k] * wv; a2 += sv[4096 + k] * wv; a3 += sv[6144 + k] * wv; a4 += sv[8192 + k] * wv; }
.LBB0_63:
	s_waitcnt vmcnt(0)
	v_add_co_u32_e32 v152, vcc, s30, v26
	s_nop 1
	v_addc_co_u32_e32 v153, vcc, -1, v27, vcc
	s_mov_b64 s[12:13], 0xc000
	s_mov_b64 s[18:19], 0xc0000
	v_lshl_add_u64 v[154:155], v[152:153], 0, s[12:13]
	v_lshl_add_u64 v[156:157], v[154:155], 0, s[12:13]
	v_lshl_add_u64 v[158:159], v[156:157], 0, s[12:13]
	v_lshl_add_u64 v[160:161], v[158:159], 0, s[12:13]
	v_lshl_add_u64 v[162:163], v[160:161], 0, s[12:13]
	v_lshl_add_u64 v[164:165], v[162:163], 0, s[12:13]
	v_lshl_add_u64 v[166:167], v[164:165], 0, s[12:13]
	v_lshl_add_u64 v[168:169], v[166:167], 0, s[12:13]
	v_lshl_add_u64 v[170:171], v[168:169], 0, s[12:13]
	v_lshl_add_u64 v[172:173], v[170:171], 0, s[12:13]
	v_lshl_add_u64 v[174:175], v[172:173], 0, s[12:13]
	v_lshl_add_u64 v[176:177], v[174:175], 0, s[12:13]
	v_lshl_add_u64 v[178:179], v[176:177], 0, s[12:13]
	v_lshl_add_u64 v[180:181], v[178:179], 0, s[12:13]
	v_lshl_add_u64 v[182:183], v[180:181], 0, s[12:13]
	global_load_dwordx4 v[84:87], v[152:153], off nt
	global_load_dwordx4 v[88:91], v[154:155], off nt
	global_load_dwordx4 v[92:95], v[156:157], off nt
	global_load_dwordx4 v[96:99], v[158:159], off nt
	global_load_dwordx4 v[100:103], v[160:161], off nt
	global_load_dwordx4 v[104:107], v[162:163], off nt
	global_load_dwordx4 v[108:111], v[164:165], off nt
	global_load_dwordx4 v[112:115], v[166:167], off nt
	global_load_dwordx4 v[116:119], v[168:169], off nt
	global_load_dwordx4 v[120:123], v[170:171], off nt
	global_load_dwordx4 v[124:127], v[172:173], off nt
	global_load_dwordx4 v[132:135], v[174:175], off nt
	global_load_dwordx4 v[136:139], v[176:177], off nt
	global_load_dwordx4 v[140:143], v[178:179], off nt
	global_load_dwordx4 v[144:147], v[180:181], off nt
	global_load_dwordx4 v[148:151], v[182:183], off nt
	s_mov_b32 s8, 7
.Lpm1_loop:
	ds_read2st64_b32 v[40:41], v33 offset1:32
	ds_read2st64_b32 v[42:43], v33 offset0:64 offset1:96
	ds_read_b32 v44, v33 offset:32768
	s_waitcnt lgkmcnt(2)
	v_mov_b32_e32 v46, v41
	s_waitcnt lgkmcnt(1)
	v_mov_b32_e32 v48, v43
	s_waitcnt vmcnt(15)
	v_pk_fma_f32 v[4:5], v[86:87], v[40:41], v[4:5] op_sel_hi:[1,0,1]
	v_pk_fma_f32 v[2:3], v[84:85], v[40:41], v[2:3] op_sel_hi:[1,0,1]
	v_pk_fma_f32 v[20:21], v[86:87], v[46:47], v[20:21] op_sel_hi:[1,0,1]
	v_pk_fma_f32 v[18:19], v[84:85], v[46:47], v[18:19] op_sel_hi:[1,0,1]
	v_pk_fma_f32 v[16:17], v[86:87], v[42:43], v[16:17] op_sel_hi:[1,0,1]
	v_pk_fma_f32 v[14:15], v[84:85], v[42:43], v[14:15] op_sel_hi:[1,0,1]
	v_pk_fma_f32 v[12:13], v[86:87], v[48:49], v[12:13] op_sel_hi:[1,0,1]
	v_pk_fma_f32 v[10:11], v[84:85], v[48:49], v[10:11] op_sel_hi:[1,0,1]
	s_waitcnt lgkmcnt(0)
	v_pk_fma_f32 v[8:9], v[86:87], v[44:45], v[8:9] op_sel_hi:[1,0,1]
	v_pk_fma_f32 v[6:7], v[84:85], v[44:45], v[6:7] op_sel_hi:[1,0,1]
	v_lshl_add_u64 v[152:153], v[152:153], 0, s[18:19]
	global_load_dwordx4 v[84:87], v[152:153], off nt
	v_add_u32_e32 v35, 4, v33
	ds_read2st64_b32 v[40:41], v35 offset1:32
	ds_read2st64_b32 v[42:43], v35 offset0:64 offset1:96
	ds_read_b32 v44, v33 offset:32772
	s_waitcnt lgkmcnt(2)
	v_mov_b32_e32 v46, v41
	s_waitcnt lgkmcnt(1)
	v_mov_b32_e32 v48, v43
	s_waitcnt vmcnt(15)
	v_pk_fma_f32 v[4:5], v[90:91], v[40:41], v[4:5] op_sel_hi:[1,0,1]
	v_pk_fma_f32 v[2:3], v[88:89], v[40:41], v[2:3] op_sel_hi:[1,0,1]
	v_pk_fma_f32 v[20:21], v[90:91], v[46:47], v[20:21] op_sel_hi:[1,0,1]
	v_pk_fma_f32 v[18:19], v[88:89], v[46:47], v[18:19] op_sel_hi:[1,0,1]
	v_pk_fma_f32 v[16:17], v[90:91], v[42:43], v[16:17] op_sel_hi:[1,0,1]
	v_pk_fma_f32 v[14:15], v[88:89], v[42:43], v[14:15] op_sel_hi:[1,0,1]
	v_pk_fma_f32 v[12:13], v[90:91], v[48:49], v[12:13] op_sel_hi:[1,0,1]
	v_pk_fma_f32 v[10:11], v[88:89], v[48:49], v[10:11] op_sel_hi:[1,0,1]
	s_waitcnt lgkmcnt(0)
	v_pk_fma_f32 v[8:9], v[90:91], v[44:45], v[8:9] op_sel_hi:[1,0,1]
	v_pk_fma_f32 v[6:7], v[88:89], v[44:45], v[6:7] op_sel_hi:[1,0,1]
	v_lshl_add_u64 v[154:155], v[154:155], 0, s[18:19]
	global_load_dwordx4 v[88:91], v[154:155], off nt
	v_add_u32_e32 v35, 8, v33
	ds_read2st64_b32 v[40:41], v35 offset1:32
	ds_read2st64_b32 v[42:43], v35 offset0:64 offset1:96
	ds_read_b32 v44, v33 offset:32776
	s_waitcnt lgkmcnt(2)
	v_mov_b32_e32 v46, v41
	s_waitcnt lgkmcnt(1)
	v_mov_b32_e32 v48, v43
	s_waitcnt vmcnt(15)
	v_pk_fma_f32 v[4:5], v[94:95], v[40:41], v[4:5] op_sel_hi:[1,0,1]
	v_pk_fma_f32 v[2:3], v[92:93], v[40:41], v[2:3] op_sel_hi:[1,0,1]
	v_pk_fma_f32 v[20:21], v[94:95], v[46:47], v[20:21] op_sel_hi:[1,0,1]
	v_pk_fma_f32 v[18:19], v[92:93], v[46:47], v[18:19] op_sel_hi:[1,0,1]
	v_pk_fma_f32 v[16:17], v[94:95], v[42:43], v[16:17] op_sel_hi:[1,0,1]
	v_pk_fma_f32 v[14:15], v[92:93], v[42:43], v[14:15] op_sel_hi:[1,0,1]
	v_pk_fma_f32 v[12:13], v[94:95], v[48:49], v[12:13] op_sel_hi:[1,0,1]
	v_pk_fma_f32 v[10:11], v[92:93], v[48:49], v[10:11] op_sel_hi:[1,0,1]
	s_waitcnt lgkmcnt(0)
	v_pk_fma_f32 v[8:9], v[94:95], v[44:45], v[8:9] op_sel_hi:[1,0,1]
	v_pk_fma_f32 v[6:7], v[92:93], v[44:45], v[6:7] op_sel_hi:[1,0,1]
	v_lshl_add_u64 v[156:157], v[156:157], 0, s[18:19]
	global_load_dwordx4 v[92:95], v[156:157], off nt
	v_add_u32_e32 v35, 12, v33
	ds_read2st64_b32 v[40:41], v35 offset1:32
	ds_read2st64_b32 v[42:43], v35 offset0:64 offset1:96
	ds_read_b32 v44, v33 offset:32780
	s_waitcnt lgkmcnt(2)
	v_mov_b32_e32 v46, v41
	s_waitcnt lgkmcnt(1)
	v_mov_b32_e32 v48, v43
	s_waitcnt vmcnt(15)
	v_pk_fma_f32 v[4:5], v[98:99], v[40:41], v[4:5] op_sel_hi:[1,0,1]
	v_pk_fma_f32 v[2:3], v[96:97], v[40:41], v[2:3] op_sel_hi:[1,0,1]
	v_pk_fma_f32 v[20:21], v[98:99], v[46:47], v[20:21] op_sel_hi:[1,0,1]
	v_pk_fma_f32 v[18:19], v[96:97], v[46:47], v[18:19] op_sel_hi:[1,0,1]
	v_pk_fma_f32 v[16:17], v[98:99], v[42:43], v[16:17] op_sel_hi:[1,0,1]
	v_pk_fma_f32 v[14:15], v[96:97], v[42:43], v[14:15] op_sel_hi:[1,0,1]
	v_pk_fma_f32 v[12:13], v[98:99], v[48:49], v[12:13] op_sel_hi:[1,0,1]
	v_pk_fma_f32 v[10:11], v[96:97], v[48:49], v[10:11] op_sel_hi:[1,0,1]
	s_waitcnt lgkmcnt(0)
;     DI const float* inp(int i) const { return as_global(P.in[i]); }
; DI void p_mod(const Frame& F) {
;     ...
;         const float* w = F.inp(4) + (size_t)l * 2048 * 12288 + colb + c4 * 4;
;         f32x4 a0 = {0.f, 0.f, 0.f, 0.f}, a1 = a0, a2 = a0, a3 = a0, a4 = a0;
; #pragma unroll 16
;         for (int k = kg * 128; k < kg * 128 + 128; ++k) { const f32x4 wv = __builtin_nontemporal_load((const f32x4*)(w + (size_t)k * 12288));
;             a0 += sv[k] * wv; a1 += sv[2048 + k] * wv; a2 += sv[4096 + k] * wv; a3 += sv[6144 + k] * wv; a4 += sv[8192 + k] * wv; }
	v_pk_fma_f32 v[8:9], v[98:99], v[44:45], v[8:9] op_sel_hi:[1,0,1]
	v_pk_fma_f32 v[6:7], v[96:97], v[44:45], v[6:7] op_sel_hi:[1,0,1]
	v_lshl_add_u64 v[158:159], v[158:159], 0, s[18:19]
	global_load_dwordx4 v[96:99], v[158:159], off nt
	v_add_u32_e32 v35, 16, v33
	ds_read2st64_b32 v[40:41], v35 offset1:32
	ds_read2st64_b32 v[42:43], v35 offset0:64 offset1:96
	ds_read_b32 v44, v33 offset:32784
	s_waitcnt lgkmcnt(2)
	v_mov_b32_e32 v46, v41
	s_waitcnt lgkmcnt(1)
	v_mov_b32_e32 v48, v43
	s_waitcnt vmcnt(15)
	v_pk_fma_f32 v[4:5], v[102:103], v[40:41], v[4:5] op_sel_hi:[1,0,1]
	v_pk_fma_f32 v[2:3], v[100:101], v[40:41], v[2:3] op_sel_hi:[1,0,1]
	v_pk_fma_f32 v[20:21], v[102:103], v[46:47], v[20:21] op_sel_hi:[1,0,1]
	v_pk_fma_f32 v[18:19], v[100:101], v[46:47], v[18:19] op_sel_hi:[1,0,1]
	v_pk_fma_f32 v[16:17], v[102:103], v[42:43], v[16:17] op_sel_hi:[1,0,1]
	v_pk_fma_f32 v[14:15], v[100:101], v[42:43], v[14:15] op_sel_hi:[1,0,1]
	v_pk_fma_f32 v[12:13], v[102:103], v[48:49], v[12:13] op_sel_hi:[1,0,1]
	v_pk_fma_f32 v[10:11], v[100:101], v[48:49], v[10:11] op_sel_hi:[1,0,1]
	s_waitcnt lgkmcnt(0)
	v_pk_fma_f32 v[8:9], v[102:103], v[44:45], v[8:9] op_sel_hi:[1,0,1]
	v_pk_fma_f32 v[6:7], v[100:101], v[44:45], v[6:7] op_sel_hi:[1,0,1]
	v_lshl_add_u64 v[160:161], v[160:161], 0, s[18:19]
	global_load_dwordx4 v[100:103], v[160:161], off nt
	v_add_u32_e32 v35, 20, v33
	ds_read2st64_b32 v[40:41], v35 offset1:32
	ds_read2st64_b32 v[42:43], v35 offset0:64 offset1:96
	ds_read_b32 v44, v33 offset:32788
	s_waitcnt lgkmcnt(2)
	v_mov_b32_e32 v46, v41
	s_waitcnt lgkmcnt(1)
	v_mov_b32_e32 v48, v43
	s_waitcnt vmcnt(15)
	v_pk_fma_f32 v[4:5], v[106:107], v[40:41], v[4:5] op_sel_hi:[1,0,1]
	v_pk_fma_f32 v[2:3], v[104:105], v[40:41], v[2:3] op_sel_hi:[1,0,1]
	v_pk_fma_f32 v[20:21], v[106:107], v[46:47], v[20:21] op_sel_hi:[1,0,1]
	v_pk_fma_f32 v[18:19], v[104:105], v[46:47], v[18:19] op_sel_hi:[1,0,1]
	v_pk_fma_f32 v[16:17], v[106:107], v[42:43], v[16:17] op_sel_hi:[1,0,1]
	v_pk_fma_f32 v[14:15], v[104:105], v[42:43], v[14:15] op_sel_hi:[1,0,1]
	v_pk_fma_f32 v[12:13], v[106:107], v[48:49], v[12:13] op_sel_hi:[1,0,1]
	v_pk_fma_f32 v[10:11], v[104:105], v[48:49], v[10:11] op_sel_hi:[1,0,1]
	s_waitcnt lgkmcnt(0)
	v_pk_fma_f32 v[8:9], v[106:107], v[44:45], v[8:9] op_sel_hi:[1,0,1]
	v_pk_fma_f32 v[6:7], v[104:105], v[44:45], v[6:7] op_sel_hi:[1,0,1]
	v_lshl_add_u64 v[162:163], v[162:163], 0, s[18:19]
	global_load_dwordx4 v[104:107], v[162:163], off nt
	v_add_u32_e32 v35, 24, v33
	ds_read2st64_b32 v[40:41], v35 offset1:32
	ds_read2st64_b32 v[42:43], v35 offset0:64 offset1:96
	ds_read_b32 v44, v33 offset:32792
	s_waitcnt lgkmcnt(2)
	v_mov_b32_e32 v46, v41
	s_waitcnt lgkmcnt(1)
	v_mov_b32_e32 v48, v43
	s_waitcnt vmcnt(15)
	v_pk_fma_f32 v[4:5], v[110:111], v[40:41], v[4:5] op_sel_hi:[1,0,1]
	v_pk_fma_f32 v[2:3], v[108:109], v[40:41], v[2:3] op_sel_hi:[1,0,1]
	v_pk_fma_f32 v[20:21], v[110:111], v[46:47], v[20:21] op_sel_hi:[1,0,1]
	v_pk_fma_f32 v[18:19], v[108:109], v[46:47], v[18:19] op_sel_hi:[1,0,1]
	v_pk_fma_f32 v[16:17], v[110:111], v[42:43], v[16:17] op_sel_hi:[1,0,1]
	v_pk_fma_f32 v[14:15], v[108:109], v[42:43], v[14:15] op_sel_hi:[1,0,1]
	v_pk_fma_f32 v[12:13], v[110:111], v[48:49], v[12:13] op_sel_hi:[1,0,1]
	v_pk_fma_f32 v[10:11], v[108:109], v[48:49], v[10:11] op_sel_hi:[1,0,1]
	s_waitcnt lgkmcnt(0)
	v_pk_fma_f32 v[8:9], v[110:111], v[44:45], v[8:9] op_sel_hi:[1,0,1]
	v_pk_fma_f32 v[6:7], v[108:109], v[44:45], v[6:7] op_sel_hi:[1,0,1]
	v_lshl_add_u64 v[164:165], v[164:165], 0, s[18:19]
	global_load_dwordx4 v[108:111], v[164:165], off nt
	v_add_u32_e32 v35, 28, v33
	ds_read2st64_b32 v[40:41], v35 offset1:32
	ds_read2st64_b32 v[42:43], v35 offset0:64 offset1:96
	ds_read_b32 v44, v33 offset:32796
	s_waitcnt lgkmcnt(2)
	v_mov_b32_e32 v46, v41
	s_waitcnt lgkmcnt(1)
	v_mov_b32_e32 v48, v43
	s_waitcnt vmcnt(15)
	v_pk_fma_f32 v[4:5], v[114:115], v[40:41], v[4:5] op_sel_hi:[1,0,1]
	v_pk_fma_f32 v[2:3], v[112:113], v[40:41], v[2:3] op_sel_hi:[1,0,1]
	v_pk_fma_f32 v[20:21], v[114:115], v[46:47], v[20:21] op_sel_hi:[1,0,1]
	v_pk_fma_f32 v[18:19], v[112:113], v[46:47], v[18:19] op_sel_hi:[1,0,1]
	v_pk_fma_f32 v[16:17], v[114:115], v[42:43], v[16:17] op_sel_hi:[1,0,1]
	v_pk_fma_f32 v[14:15], v[112:113], v[42:43], v[14:15] op_sel_hi:[1,0,1]
	v_pk_fma_f32 v[12:13], v[114:115], v[48:49], v[12:13] op_sel_hi:[1,0,1]
	v_pk_fma_f32 v[10:11], v[112:113], v[48:49], v[10:11] op_sel_hi:[1,0,1]
	s_waitcnt lgkmcnt(0)
	v_pk_fma_f32 v[8:9], v[114:115], v[44:45], v[8:9] op_sel_hi:[1,0,1]
	v_pk_fma_f32 v[6:7], v[112:113], v[44:45], v[6:7] op_sel_hi:[1,0,1]
	v_lshl_add_u64 v[166:167], v[166:167], 0, s[18:19]
	global_load_dwordx4 v[112:115], v[166:167], off nt
	v_add_u32_e32 v35, 32, v33
	ds_read2st64_b32 v[40:41], v35 offset1:32
	ds_read2st64_b32 v[42:43], v35 offset0:64 offset1:96
	ds_read_b32 v44, v33 offset:32800
	s_waitcnt lgkmcnt(2)
	v_mov_b32_e32 v46, v41
	s_waitcnt lgkmcnt(1)
	v_mov_b32_e32 v48, v43
	s_waitcnt vmcnt(15)
	v_pk_fma_f32 v[4:5], v[118:119], v[40:41], v[4:5] op_sel_hi:[1,0,1]
	v_pk_fma_f32 v[2:3], v[116:117], v[40:41], v[2:3] op_sel_hi:[1,0,1]
	v_pk_fma_f32 v[20:21], v[118:119], v[46:47], v[20:21] op_sel_hi:[1,0,1]
	v_pk_fma_f32 v[18:19], v[116:117], v[46:47], v[18:19] op_sel_hi:[1,0,1]
	v_pk_fma_f32 v[16:17], v[118:119], v[42:43], v[16:17] op_sel_hi:[1,0,1]
	v_pk_fma_f32 v[14:15], v[116:117], v[42:43], v[14:15] op_sel_hi:[1,0,1]
	v_pk_fma_f32 v[12:13], v[118:119], v[48:49], v[12:13] op_sel_hi:[1,0,1]
	v_pk_fma_f32 v[10:11], v[116:117], v[48:49], v[10:11] op_sel_hi:[1,0,1]
	s_waitcnt lgkmcnt(0)
;     DI const float* inp(int i) const { return as_global(P.in[i]); }
; DI void p_mod(const Frame& F) {
;     ...
;         const float* w = F.inp(4) + (size_t)l * 2048 * 12288 + colb + c4 * 4;
;         f32x4 a0 = {0.f, 0.f, 0.f, 0.f}, a1 = a0, a2 = a0, a3 = a0, a4 = a0;
; #pragma unroll 16
;         for (int k = kg * 128; k < kg * 128 + 128; ++k) { const f32x4 wv = __builtin_nontemporal_load((const f32x4*)(w + (size_t)k * 12288));
;             a0 += sv[k] * wv; a1 += sv[2048 + k] * wv; a2 += sv[4096 + k] * wv; a3 += sv[6144 + k] * wv; a4 += sv[8192 + k] * wv; }
	v_pk_fma_f32 v[8:9], v[118:119], v[44:45], v[8:9] op_sel_hi:[1,0,1]
	v_pk_fma_f32 v[6:7], v[116:117], v[44:45], v[6:7] op_sel_hi:[1,0,1]
	v_lshl_add_u64 v[168:169], v[168:169], 0, s[18:19]
	global_load_dwordx4 v[116:119], v[168:169], off nt
	v_add_u32_e32 v35, 36, v33
	ds_read2st64_b32 v[40:41], v35 offset1:32
	ds_read2st64_b32 v[42:43], v35 offset0:64 offset1:96
	ds_read_b32 v44, v33 offset:32804
	s_waitcnt lgkmcnt(2)
	v_mov_b32_e32 v46, v41
	s_waitcnt lgkmcnt(1)
	v_mov_b32_e32 v48, v43
	s_waitcnt vmcnt(15)
	v_pk_fma_f32 v[4:5], v[122:123], v[40:41], v[4:5] op_sel_hi:[1,0,1]
	v_pk_fma_f32 v[2:3], v[120:121], v[40:41], v[2:3] op_sel_hi:[1,0,1]
	v_pk_fma_f32 v[20:21], v[122:123], v[46:47], v[20:21] op_sel_hi:[1,0,1]
	v_pk_fma_f32 v[18:19], v[120:121], v[46:47], v[18:19] op_sel_hi:[1,0,1]
	v_pk_fma_f32 v[16:17], v[122:123], v[42:43], v[16:17] op_sel_hi:[1,0,1]
	v_pk_fma_f32 v[14:15], v[120:121], v[42:43], v[14:15] op_sel_hi:[1,0,1]
	v_pk_fma_f32 v[12:13], v[122:123], v[48:49], v[12:13] op_sel_hi:[1,0,1]
	v_pk_fma_f32 v[10:11], v[120:121], v[48:49], v[10:11] op_sel_hi:[1,0,1]
	s_waitcnt lgkmcnt(0)
	v_pk_fma_f32 v[8:9], v[122:123], v[44:45], v[8:9] op_sel_hi:[1,0,1]
	v_pk_fma_f32 v[6:7], v[120:121], v[44:45], v[6:7] op_sel_hi:[1,0,1]
	v_lshl_add_u64 v[170:171], v[170:171], 0, s[18:19]
	global_load_dwordx4 v[120:123], v[170:171], off nt
	v_add_u32_e32 v35, 40, v33
	ds_read2st64_b32 v[40:41], v35 offset1:32
	ds_read2st64_b32 v[42:43], v35 offset0:64 offset1:96
	ds_read_b32 v44, v33 offset:32808
	s_waitcnt lgkmcnt(2)
	v_mov_b32_e32 v46, v41
	s_waitcnt lgkmcnt(1)
	v_mov_b32_e32 v48, v43
	s_waitcnt vmcnt(15)
	v_pk_fma_f32 v[4:5], v[126:127], v[40:41], v[4:5] op_sel_hi:[1,0,1]
	v_pk_fma_f32 v[2:3], v[124:125], v[40:41], v[2:3] op_sel_hi:[1,0,1]
	v_pk_fma_f32 v[20:21], v[126:127], v[46:47], v[20:21] op_sel_hi:[1,0,1]
	v_pk_fma_f32 v[18:19], v[124:125], v[46:47], v[18:19] op_sel_hi:[1,0,1]
	v_pk_fma_f32 v[16:17], v[126:127], v[42:43], v[16:17] op_sel_hi:[1,0,1]
	v_pk_fma_f32 v[14:15], v[124:125], v[42:43], v[14:15] op_sel_hi:[1,0,1]
	v_pk_fma_f32 v[12:13], v[126:127], v[48:49], v[12:13] op_sel_hi:[1,0,1]
	v_pk_fma_f32 v[10:11], v[124:125], v[48:49], v[10:11] op_sel_hi:[1,0,1]
	s_waitcnt lgkmcnt(0)
	v_pk_fma_f32 v[8:9], v[126:127], v[44:45], v[8:9] op_sel_hi:[1,0,1]
	v_pk_fma_f32 v[6:7], v[124:125], v[44:45], v[6:7] op_sel_hi:[1,0,1]
	v_lshl_add_u64 v[172:173], v[172:173], 0, s[18:19]
	global_load_dwordx4 v[124:127], v[172:173], off nt
	v_add_u32_e32 v35, 44, v33
	ds_read2st64_b32 v[40:41], v35 offset1:32
	ds_read2st64_b32 v[42:43], v35 offset0:64 offset1:96
	ds_read_b32 v44, v33 offset:32812
	s_waitcnt lgkmcnt(2)
	v_mov_b32_e32 v46, v41
	s_waitcnt lgkmcnt(1)
	v_mov_b32_e32 v48, v43
	s_waitcnt vmcnt(15)
	v_pk_fma_f32 v[4:5], v[134:135], v[40:41], v[4:5] op_sel_hi:[1,0,1]
	v_pk_fma_f32 v[2:3], v[132:133], v[40:41], v[2:3] op_sel_hi:[1,0,1]
	v_pk_fma_f32 v[20:21], v[134:135], v[46:47], v[20:21] op_sel_hi:[1,0,1]
	v_pk_fma_f32 v[18:19], v[132:133], v[46:47], v[18:19] op_sel_hi:[1,0,1]
	v_pk_fma_f32 v[16:17], v[134:135], v[42:43], v[16:17] op_sel_hi:[1,0,1]
	v_pk_fma_f32 v[14:15], v[132:133], v[42:43], v[14:15] op_sel_hi:[1,0,1]
	v_pk_fma_f32 v[12:13], v[134:135], v[48:49], v[12:13] op_sel_hi:[1,0,1]
	v_pk_fma_f32 v[10:11], v[132:133], v[48:49], v[10:11] op_sel_hi:[1,0,1]
	s_waitcnt lgkmcnt(0)
	v_pk_fma_f32 v[8:9], v[134:135], v[44:45], v[8:9] op_sel_hi:[1,0,1]
	v_pk_fma_f32 v[6:7], v[132:133], v[44:45], v[6:7] op_sel_hi:[1,0,1]
	v_lshl_add_u64 v[174:175], v[174:175], 0, s[18:19]
	global_load_dwordx4 v[132:135], v[174:175], off nt
	v_add_u32_e32 v35, 48, v33
	ds_read2st64_b32 v[40:41], v35 offset1:32
	ds_read2st64_b32 v[42:43], v35 offset0:64 offset1:96
	ds_read_b32 v44, v33 offset:32816
	s_waitcnt lgkmcnt(2)
	v_mov_b32_e32 v46, v41
	s_waitcnt lgkmcnt(1)
	v_mov_b32_e32 v48, v43
	s_waitcnt vmcnt(15)
	v_pk_fma_f32 v[4:5], v[138:139], v[40:41], v[4:5] op_sel_hi:[1,0,1]
	v_pk_fma_f32 v[2:3], v[136:137], v[40:41], v[2:3] op_sel_hi:[1,0,1]
	v_pk_fma_f32 v[20:21], v[138:139], v[46:47], v[20:21] op_sel_hi:[1,0,1]
	v_pk_fma_f32 v[18:19], v[136:137], v[46:47], v[18:19] op_sel_hi:[1,0,1]
	v_pk_fma_f32 v[16:17], v[138:139], v[42:43], v[16:17] op_sel_hi:[1,0,1]
	v_pk_fma_f32 v[14:15], v[136:137], v[42:43], v[14:15] op_sel_hi:[1,0,1]
	v_pk_fma_f32 v[12:13], v[138:139], v[48:49], v[12:13] op_sel_hi:[1,0,1]
	v_pk_fma_f32 v[10:11], v[136:137], v[48:49], v[10:11] op_sel_hi:[1,0,1]
	s_waitcnt lgkmcnt(0)
	v_pk_fma_f32 v[8:9], v[138:139], v[44:45], v[8:9] op_sel_hi:[1,0,1]
	v_pk_fma_f32 v[6:7], v[136:137], v[44:45], v[6:7] op_sel_hi:[1,0,1]
	v_lshl_add_u64 v[176:177], v[176:177], 0, s[18:19]
	global_load_dwordx4 v[136:139], v[176:177], off nt
	v_add_u32_e32 v35, 52, v33
	ds_read2st64_b32 v[40:41], v35 offset1:32
	ds_read2st64_b32 v[42:43], v35 offset0:64 offset1:96
	ds_read_b32 v44, v33 offset:32820
	s_waitcnt lgkmcnt(2)
	v_mov_b32_e32 v46, v41
	s_waitcnt lgkmcnt(1)
	v_mov_b32_e32 v48, v43
	s_waitcnt vmcnt(15)
	v_pk_fma_f32 v[4:5], v[142:143], v[40:41], v[4:5] op_sel_hi:[1,0,1]
	v_pk_fma_f32 v[2:3], v[140:141], v[40:41], v[2:3] op_sel_hi:[1,0,1]
	v_pk_fma_f32 v[20:21], v[142:143], v[46:47], v[20:21] op_sel_hi:[1,0,1]
	v_pk_fma_f32 v[18:19], v[140:141], v[46:47], v[18:19] op_sel_hi:[1,0,1]
	v_pk_fma_f32 v[16:17], v[142:143], v[42:43], v[16:17] op_sel_hi:[1,0,1]
	v_pk_fma_f32 v[14:15], v[140:141], v[42:43], v[14:15] op_sel_hi:[1,0,1]
	v_pk_fma_f32 v[12:13], v[142:143], v[48:49], v[12:13] op_sel_hi:[1,0,1]
	v_pk_fma_f32 v[10:11], v[140:141], v[48:49], v[10:11] op_sel_hi:[1,0,1]
	s_waitcnt lgkmcnt(0)
; DI void p_mod(const Frame& F) {
;     ...
;         for (int k = kg * 128; k < kg * 128 + 128; ++k) { const f32x4 wv = __builtin_nontemporal_load((const f32x4*)(w + (size_t)k * 12288));
;             a0 += sv[k] * wv; a1 += sv[2048 + k] * wv; a2 += sv[4096 + k] * wv; a3 += sv[6144 + k] * wv; a4 += sv[8192 + k] * wv; }
	v_pk_fma_f32 v[8:9], v[142:143], v[44:45], v[8:9] op_sel_hi:[1,0,1]
	v_pk_fma_f32 v[6:7], v[140:141], v[44:45], v[6:7] op_sel_hi:[1,0,1]
	v_lshl_add_u64 v[178:179], v[178:179], 0, s[18:19]
	global_load_dwordx4 v[140:143], v[178:179], off nt
	v_add_u32_e32 v35, 56, v33
	ds_read2st64_b32 v[40:41], v35 offset1:32
	ds_read2st64_b32 v[42:43], v35 offset0:64 offset1:96
	ds_read_b32 v44, v33 offset:32824
	s_waitcnt lgkmcnt(2)
	v_mov_b32_e32 v46, v41
	s_waitcnt lgkmcnt(1)
	v_mov_b32_e32 v48, v43
	s_waitcnt vmcnt(15)
	v_pk_fma_f32 v[4:5], v[146:147], v[40:41], v[4:5] op_sel_hi:[1,0,1]
	v_pk_fma_f32 v[2:3], v[144:145], v[40:41], v[2:3] op_sel_hi:[1,0,1]
	v_pk_fma_f32 v[20:21], v[146:147], v[46:47], v[20:21] op_sel_hi:[1,0,1]
	v_pk_fma_f32 v[18:19], v[144:145], v[46:47], v[18:19] op_sel_hi:[1,0,1]
	v_pk_fma_f32 v[16:17], v[146:147], v[42:43], v[16:17] op_sel_hi:[1,0,1]
	v_pk_fma_f32 v[14:15], v[144:145], v[42:43], v[14:15] op_sel_hi:[1,0,1]
	v_pk_fma_f32 v[12:13], v[146:147], v[48:49], v[12:13] op_sel_hi:[1,0,1]
	v_pk_fma_f32 v[10:11], v[144:145], v[48:49], v[10:11] op_sel_hi:[1,0,1]
	s_waitcnt lgkmcnt(0)
	v_pk_fma_f32 v[8:9], v[146:147], v[44:45], v[8:9] op_sel_hi:[1,0,1]
	v_pk_fma_f32 v[6:7], v[144:145], v[44:45], v[6:7] op_sel_hi:[1,0,1]
	v_lshl_add_u64 v[180:181], v[180:181], 0, s[18:19]
	global_load_dwordx4 v[144:147], v[180:181], off nt
	v_add_u32_e32 v35, 60, v33
	ds_read2st64_b32 v[40:41], v35 offset1:32
	ds_read2st64_b32 v[42:43], v35 offset0:64 offset1:96
	ds_read_b32 v44, v33 offset:32828
	s_waitcnt lgkmcnt(2)
	v_mov_b32_e32 v46, v41
	s_waitcnt lgkmcnt(1)
	v_mov_b32_e32 v48, v43
	s_waitcnt vmcnt(15)
	v_pk_fma_f32 v[4:5], v[150:151], v[40:41], v[4:5] op_sel_hi:[1,0,1]
	v_pk_fma_f32 v[2:3], v[148:149], v[40:41], v[2:3] op_sel_hi:[1,0,1]
	v_pk_fma_f32 v[20:21], v[150:151], v[46:47], v[20:21] op_sel_hi:[1,0,1]
	v_pk_fma_f32 v[18:19], v[148:149], v[46:47], v[18:19] op_sel_hi:[1,0,1]
	v_pk_fma_f32 v[16:17], v[150:151], v[42:43], v[16:17] op_sel_hi:[1,0,1]
	v_pk_fma_f32 v[14:15], v[148:149], v[42:43], v[14:15] op_sel_hi:[1,0,1]
	v_pk_fma_f32 v[12:13], v[150:151], v[48:49], v[12:13] op_sel_hi:[1,0,1]
	v_pk_fma_f32 v[10:11], v[148:149], v[48:49], v[10:11] op_sel_hi:[1,0,1]
	s_waitcnt lgkmcnt(0)
	v_pk_fma_f32 v[8:9], v[150:151], v[44:45], v[8:9] op_sel_hi:[1,0,1]
	v_pk_fma_f32 v[6:7], v[148:149], v[44:45], v[6:7] op_sel_hi:[1,0,1]
	v_lshl_add_u64 v[182:183], v[182:183], 0, s[18:19]
	global_load_dwordx4 v[148:151], v[182:183], off nt
	v_add_u32_e32 v33, 64, v33
	s_add_i32 s8, s8, -1
	s_cmp_lg_u32 s8, 0
	s_cbranch_scc1 .Lpm1_loop
	ds_read2st64_b32 v[40:41], v33 offset1:32
	ds_read2st64_b32 v[42:43], v33 offset0:64 offset1:96
	ds_read_b32 v44, v33 offset:32768
	s_waitcnt lgkmcnt(2)
	v_mov_b32_e32 v46, v41
	s_waitcnt lgkmcnt(1)
	v_mov_b32_e32 v48, v43
	s_waitcnt vmcnt(15)
	v_pk_fma_f32 v[4:5], v[86:87], v[40:41], v[4:5] op_sel_hi:[1,0,1]
	v_pk_fma_f32 v[2:3], v[84:85], v[40:41], v[2:3] op_sel_hi:[1,0,1]
	v_pk_fma_f32 v[20:21], v[86:87], v[46:47], v[20:21] op_sel_hi:[1,0,1]
	v_pk_fma_f32 v[18:19], v[84:85], v[46:47], v[18:19] op_sel_hi:[1,0,1]
	v_pk_fma_f32 v[16:17], v[86:87], v[42:43], v[16:17] op_sel_hi:[1,0,1]
	v_pk_fma_f32 v[14:15], v[84:85], v[42:43], v[14:15] op_sel_hi:[1,0,1]
	v_pk_fma_f32 v[12:13], v[86:87], v[48:49], v[12:13] op_sel_hi:[1,0,1]
	v_pk_fma_f32 v[10:11], v[84:85], v[48:49], v[10:11] op_sel_hi:[1,0,1]
	s_waitcnt lgkmcnt(0)
	v_pk_fma_f32 v[8:9], v[86:87], v[44:45], v[8:9] op_sel_hi:[1,0,1]
	v_pk_fma_f32 v[6:7], v[84:85], v[44:45], v[6:7] op_sel_hi:[1,0,1]
	v_add_u32_e32 v35, 4, v33
	ds_read2st64_b32 v[40:41], v35 offset1:32
	ds_read2st64_b32 v[42:43], v35 offset0:64 offset1:96
	ds_read_b32 v44, v33 offset:32772
	s_waitcnt lgkmcnt(2)
	v_mov_b32_e32 v46, v41
	s_waitcnt lgkmcnt(1)
	v_mov_b32_e32 v48, v43
	s_waitcnt vmcnt(14)
	v_pk_fma_f32 v[4:5], v[90:91], v[40:41], v[4:5] op_sel_hi:[1,0,1]
	v_pk_fma_f32 v[2:3], v[88:89], v[40:41], v[2:3] op_sel_hi:[1,0,1]
	v_pk_fma_f32 v[20:21], v[90:91], v[46:47], v[20:21] op_sel_hi:[1,0,1]
	v_pk_fma_f32 v[18:19], v[88:89], v[46:47], v[18:19] op_sel_hi:[1,0,1]
	v_pk_fma_f32 v[16:17], v[90:91], v[42:43], v[16:17] op_sel_hi:[1,0,1]
	v_pk_fma_f32 v[14:15], v[88:89], v[42:43], v[14:15] op_sel_hi:[1,0,1]
	v_pk_fma_f32 v[12:13], v[90:91], v[48:49], v[12:13] op_sel_hi:[1,0,1]
	v_pk_fma_f32 v[10:11], v[88:89], v[48:49], v[10:11] op_sel_hi:[1,0,1]
	s_waitcnt lgkmcnt(0)
	v_pk_fma_f32 v[8:9], v[90:91], v[44:45], v[8:9] op_sel_hi:[1,0,1]
	v_pk_fma_f32 v[6:7], v[88:89], v[44:45], v[6:7] op_sel_hi:[1,0,1]
	v_add_u32_e32 v35, 8, v33
	ds_read2st64_b32 v[40:41], v35 offset1:32
	ds_read2st64_b32 v[42:43], v35 offset0:64 offset1:96
	ds_read_b32 v44, v33 offset:32776
	s_waitcnt lgkmcnt(2)
	v_mov_b32_e32 v46, v41
	s_waitcnt lgkmcnt(1)
	v_mov_b32_e32 v48, v43
	s_waitcnt vmcnt(13)
	v_pk_fma_f32 v[4:5], v[94:95], v[40:41], v[4:5] op_sel_hi:[1,0,1]
	v_pk_fma_f32 v[2:3], v[92:93], v[40:41], v[2:3] op_sel_hi:[1,0,1]
	v_pk_fma_f32 v[20:21], v[94:95], v[46:47], v[20:21] op_sel_hi:[1,0,1]
	v_pk_fma_f32 v[18:19], v[92:93], v[46:47], v[18:19] op_sel_hi:[1,0,1]
	v_pk_fma_f32 v[16:17], v[94:95], v[42:43], v[16:17] op_sel_hi:[1,0,1]
	v_pk_fma_f32 v[14:15], v[92:93], v[42:43], v[14:15] op_sel_hi:[1,0,1]
	v_pk_fma_f32 v[12:13], v[94:95], v[48:49], v[12:13] op_sel_hi:[1,0,1]
	v_pk_fma_f32 v[10:11], v[92:93], v[48:49], v[10:11] op_sel_hi:[1,0,1]
	s_waitcnt lgkmcnt(0)
	v_pk_fma_f32 v[8:9], v[94:95], v[44:45], v[8:9] op_sel_hi:[1,0,1]
	v_pk_fma_f32 v[6:7], v[92:93], v[44:45], v[6:7] op_sel_hi:[1,0,1]
	v_add_u32_e32 v35, 12, v33
	ds_read2st64_b32 v[40:41], v35 offset1:32
	ds_read2st64_b32 v[42:43], v35 offset0:64 offset1:96
	ds_read_b32 v44, v33 offset:32780
	s_waitcnt lgkmcnt(2)
; DI void p_mod(const Frame& F) {
;     ...
;         for (int k = kg * 128; k < kg * 128 + 128; ++k) { const f32x4 wv = __builtin_nontemporal_load((const f32x4*)(w + (size_t)k * 12288));
;             a0 += sv[k] * wv; a1 += sv[2048 + k] * wv; a2 += sv[4096 + k] * wv; a3 += sv[6144 + k] * wv; a4 += sv[8192 + k] * wv; }
	v_mov_b32_e32 v46, v41
	s_waitcnt lgkmcnt(1)
	v_mov_b32_e32 v48, v43
	s_waitcnt vmcnt(12)
	v_pk_fma_f32 v[4:5], v[98:99], v[40:41], v[4:5] op_sel_hi:[1,0,1]
	v_pk_fma_f32 v[2:3], v[96:97], v[40:41], v[2:3] op_sel_hi:[1,0,1]
	v_pk_fma_f32 v[20:21], v[98:99], v[46:47], v[20:21] op_sel_hi:[1,0,1]
	v_pk_fma_f32 v[18:19], v[96:97], v[46:47], v[18:19] op_sel_hi:[1,0,1]
	v_pk_fma_f32 v[16:17], v[98:99], v[42:43], v[16:17] op_sel_hi:[1,0,1]
	v_pk_fma_f32 v[14:15], v[96:97], v[42:43], v[14:15] op_sel_hi:[1,0,1]
	v_pk_fma_f32 v[12:13], v[98:99], v[48:49], v[12:13] op_sel_hi:[1,0,1]
	v_pk_fma_f32 v[10:11], v[96:97], v[48:49], v[10:11] op_sel_hi:[1,0,1]
	s_waitcnt lgkmcnt(0)
	v_pk_fma_f32 v[8:9], v[98:99], v[44:45], v[8:9] op_sel_hi:[1,0,1]
	v_pk_fma_f32 v[6:7], v[96:97], v[44:45], v[6:7] op_sel_hi:[1,0,1]
	v_add_u32_e32 v35, 16, v33
	ds_read2st64_b32 v[40:41], v35 offset1:32
	ds_read2st64_b32 v[42:43], v35 offset0:64 offset1:96
	ds_read_b32 v44, v33 offset:32784
	s_waitcnt lgkmcnt(2)
	v_mov_b32_e32 v46, v41
	s_waitcnt lgkmcnt(1)
	v_mov_b32_e32 v48, v43
	s_waitcnt vmcnt(11)
	v_pk_fma_f32 v[4:5], v[102:103], v[40:41], v[4:5] op_sel_hi:[1,0,1]
	v_pk_fma_f32 v[2:3], v[100:101], v[40:41], v[2:3] op_sel_hi:[1,0,1]
	v_pk_fma_f32 v[20:21], v[102:103], v[46:47], v[20:21] op_sel_hi:[1,0,1]
	v_pk_fma_f32 v[18:19], v[100:101], v[46:47], v[18:19] op_sel_hi:[1,0,1]
	v_pk_fma_f32 v[16:17], v[102:103], v[42:43], v[16:17] op_sel_hi:[1,0,1]
	v_pk_fma_f32 v[14:15], v[100:101], v[42:43], v[14:15] op_sel_hi:[1,0,1]
	v_pk_fma_f32 v[12:13], v[102:103], v[48:49], v[12:13] op_sel_hi:[1,0,1]
	v_pk_fma_f32 v[10:11], v[100:101], v[48:49], v[10:11] op_sel_hi:[1,0,1]
	s_waitcnt lgkmcnt(0)
	v_pk_fma_f32 v[8:9], v[102:103], v[44:45], v[8:9] op_sel_hi:[1,0,1]
	v_pk_fma_f32 v[6:7], v[100:101], v[44:45], v[6:7] op_sel_hi:[1,0,1]
	v_add_u32_e32 v35, 20, v33
	ds_read2st64_b32 v[40:41], v35 offset1:32
	ds_read2st64_b32 v[42:43], v35 offset0:64 offset1:96
	ds_read_b32 v44, v33 offset:32788
	s_waitcnt lgkmcnt(2)
	v_mov_b32_e32 v46, v41
	s_waitcnt lgkmcnt(1)
	v_mov_b32_e32 v48, v43
	s_waitcnt vmcnt(10)
	v_pk_fma_f32 v[4:5], v[106:107], v[40:41], v[4:5] op_sel_hi:[1,0,1]
	v_pk_fma_f32 v[2:3], v[104:105], v[40:41], v[2:3] op_sel_hi:[1,0,1]
	v_pk_fma_f32 v[20:21], v[106:107], v[46:47], v[20:21] op_sel_hi:[1,0,1]
	v_pk_fma_f32 v[18:19], v[104:105], v[46:47], v[18:19] op_sel_hi:[1,0,1]
	v_pk_fma_f32 v[16:17], v[106:107], v[42:43], v[16:17] op_sel_hi:[1,0,1]
	v_pk_fma_f32 v[14:15], v[104:105], v[42:43], v[14:15] op_sel_hi:[1,0,1]
	v_pk_fma_f32 v[12:13], v[106:107], v[48:49], v[12:13] op_sel_hi:[1,0,1]
	v_pk_fma_f32 v[10:11], v[104:105], v[48:49], v[10:11] op_sel_hi:[1,0,1]
	s_waitcnt lgkmcnt(0)
	v_pk_fma_f32 v[8:9], v[106:107], v[44:45], v[8:9] op_sel_hi:[1,0,1]
	v_pk_fma_f32 v[6:7], v[104:105], v[44:45], v[6:7] op_sel_hi:[1,0,1]
	v_add_u32_e32 v35, 24, v33
	ds_read2st64_b32 v[40:41], v35 offset1:32
	ds_read2st64_b32 v[42:43], v35 offset0:64 offset1:96
	ds_read_b32 v44, v33 offset:32792
	s_waitcnt lgkmcnt(2)
	v_mov_b32_e32 v46, v41
	s_waitcnt lgkmcnt(1)
	v_mov_b32_e32 v48, v43
	s_waitcnt vmcnt(9)
	v_pk_fma_f32 v[4:5], v[110:111], v[40:41], v[4:5] op_sel_hi:[1,0,1]
	v_pk_fma_f32 v[2:3], v[108:109], v[40:41], v[2:3] op_sel_hi:[1,0,1]
	v_pk_fma_f32 v[20:21], v[110:111], v[46:47], v[20:21] op_sel_hi:[1,0,1]
	v_pk_fma_f32 v[18:19], v[108:109], v[46:47], v[18:19] op_sel_hi:[1,0,1]
	v_pk_fma_f32 v[16:17], v[110:111], v[42:43], v[16:17] op_sel_hi:[1,0,1]
	v_pk_fma_f32 v[14:15], v[108:109], v[42:43], v[14:15] op_sel_hi:[1,0,1]
	v_pk_fma_f32 v[12:13], v[110:111], v[48:49], v[12:13] op_sel_hi:[1,0,1]
	v_pk_fma_f32 v[10:11], v[108:109], v[48:49], v[10:11] op_sel_hi:[1,0,1]
	s_waitcnt lgkmcnt(0)
	v_pk_fma_f32 v[8:9], v[110:111], v[44:45], v[8:9] op_sel_hi:[1,0,1]
	v_pk_fma_f32 v[6:7], v[108:109], v[44:45], v[6:7] op_sel_hi:[1,0,1]
	v_add_u32_e32 v35, 28, v33
	ds_read2st64_b32 v[40:41], v35 offset1:32
	ds_read2st64_b32 v[42:43], v35 offset0:64 offset1:96
	ds_read_b32 v44, v33 offset:32796
	s_waitcnt lgkmcnt(2)
	v_mov_b32_e32 v46, v41
	s_waitcnt lgkmcnt(1)
	v_mov_b32_e32 v48, v43
	s_waitcnt vmcnt(8)
	v_pk_fma_f32 v[4:5], v[114:115], v[40:41], v[4:5] op_sel_hi:[1,0,1]
	v_pk_fma_f32 v[2:3], v[112:113], v[40:41], v[2:3] op_sel_hi:[1,0,1]
	v_pk_fma_f32 v[20:21], v[114:115], v[46:47], v[20:21] op_sel_hi:[1,0,1]
	v_pk_fma_f32 v[18:19], v[112:113], v[46:47], v[18:19] op_sel_hi:[1,0,1]
	v_pk_fma_f32 v[16:17], v[114:115], v[42:43], v[16:17] op_sel_hi:[1,0,1]
	v_pk_fma_f32 v[14:15], v[112:113], v[42:43], v[14:15] op_sel_hi:[1,0,1]
	v_pk_fma_f32 v[12:13], v[114:115], v[48:49], v[12:13] op_sel_hi:[1,0,1]
	v_pk_fma_f32 v[10:11], v[112:113], v[48:49], v[10:11] op_sel_hi:[1,0,1]
	s_waitcnt lgkmcnt(0)
	v_pk_fma_f32 v[8:9], v[114:115], v[44:45], v[8:9] op_sel_hi:[1,0,1]
	v_pk_fma_f32 v[6:7], v[112:113], v[44:45], v[6:7] op_sel_hi:[1,0,1]
	v_add_u32_e32 v35, 32, v33
	ds_read2st64_b32 v[40:41], v35 offset1:32
	ds_read2st64_b32 v[42:43], v35 offset0:64 offset1:96
	ds_read_b32 v44, v33 offset:32800
	s_waitcnt lgkmcnt(2)
	v_mov_b32_e32 v46, v41
	s_waitcnt lgkmcnt(1)
	v_mov_b32_e32 v48, v43
	s_waitcnt vmcnt(7)
	v_pk_fma_f32 v[4:5], v[118:119], v[40:41], v[4:5] op_sel_hi:[1,0,1]
	v_pk_fma_f32 v[2:3], v[116:117], v[40:41], v[2:3] op_sel_hi:[1,0,1]
	v_pk_fma_f32 v[20:21], v[118:119], v[46:47], v[20:21] op_sel_hi:[1,0,1]
	v_pk_fma_f32 v[18:19], v[116:117], v[46:47], v[18:19] op_sel_hi:[1,0,1]
	v_pk_fma_f32 v[16:17], v[118:119], v[42:43], v[16:17] op_sel_hi:[1,0,1]
	v_pk_fma_f32 v[14:15], v[116:117], v[42:43], v[14:15] op_sel_hi:[1,0,1]
	v_pk_fma_f32 v[12:13], v[118:119], v[48:49], v[12:13] op_sel_hi:[1,0,1]
	v_pk_fma_f32 v[10:11], v[116:117], v[48:49], v[10:11] op_sel_hi:[1,0,1]
	s_waitcnt lgkmcnt(0)
; DI void p_mod(const Frame& F) {
;     ...
;         for (int k = kg * 128; k < kg * 128 + 128; ++k) { const f32x4 wv = __builtin_nontemporal_load((const f32x4*)(w + (size_t)k * 12288));
;             a0 += sv[k] * wv; a1 += sv[2048 + k] * wv; a2 += sv[4096 + k] * wv; a3 += sv[6144 + k] * wv; a4 += sv[8192 + k] * wv; }
	v_pk_fma_f32 v[8:9], v[118:119], v[44:45], v[8:9] op_sel_hi:[1,0,1]
	v_pk_fma_f32 v[6:7], v[116:117], v[44:45], v[6:7] op_sel_hi:[1,0,1]
	v_add_u32_e32 v35, 36, v33
	ds_read2st64_b32 v[40:41], v35 offset1:32
	ds_read2st64_b32 v[42:43], v35 offset0:64 offset1:96
	ds_read_b32 v44, v33 offset:32804
	s_waitcnt lgkmcnt(2)
	v_mov_b32_e32 v46, v41
	s_waitcnt lgkmcnt(1)
	v_mov_b32_e32 v48, v43
	s_waitcnt vmcnt(6)
	v_pk_fma_f32 v[4:5], v[122:123], v[40:41], v[4:5] op_sel_hi:[1,0,1]
	v_pk_fma_f32 v[2:3], v[120:121], v[40:41], v[2:3] op_sel_hi:[1,0,1]
	v_pk_fma_f32 v[20:21], v[122:123], v[46:47], v[20:21] op_sel_hi:[1,0,1]
	v_pk_fma_f32 v[18:19], v[120:121], v[46:47], v[18:19] op_sel_hi:[1,0,1]
	v_pk_fma_f32 v[16:17], v[122:123], v[42:43], v[16:17] op_sel_hi:[1,0,1]
	v_pk_fma_f32 v[14:15], v[120:121], v[42:43], v[14:15] op_sel_hi:[1,0,1]
	v_pk_fma_f32 v[12:13], v[122:123], v[48:49], v[12:13] op_sel_hi:[1,0,1]
	v_pk_fma_f32 v[10:11], v[120:121], v[48:49], v[10:11] op_sel_hi:[1,0,1]
	s_waitcnt lgkmcnt(0)
	v_pk_fma_f32 v[8:9], v[122:123], v[44:45], v[8:9] op_sel_hi:[1,0,1]
	v_pk_fma_f32 v[6:7], v[120:121], v[44:45], v[6:7] op_sel_hi:[1,0,1]
	v_add_u32_e32 v35, 40, v33
	ds_read2st64_b32 v[40:41], v35 offset1:32
	ds_read2st64_b32 v[42:43], v35 offset0:64 offset1:96
	ds_read_b32 v44, v33 offset:32808
	s_waitcnt lgkmcnt(2)
	v_mov_b32_e32 v46, v41
	s_waitcnt lgkmcnt(1)
	v_mov_b32_e32 v48, v43
	s_waitcnt vmcnt(5)
	v_pk_fma_f32 v[4:5], v[126:127], v[40:41], v[4:5] op_sel_hi:[1,0,1]
	v_pk_fma_f32 v[2:3], v[124:125], v[40:41], v[2:3] op_sel_hi:[1,0,1]
	v_pk_fma_f32 v[20:21], v[126:127], v[46:47], v[20:21] op_sel_hi:[1,0,1]
	v_pk_fma_f32 v[18:19], v[124:125], v[46:47], v[18:19] op_sel_hi:[1,0,1]
	v_pk_fma_f32 v[16:17], v[126:127], v[42:43], v[16:17] op_sel_hi:[1,0,1]
	v_pk_fma_f32 v[14:15], v[124:125], v[42:43], v[14:15] op_sel_hi:[1,0,1]
	v_pk_fma_f32 v[12:13], v[126:127], v[48:49], v[12:13] op_sel_hi:[1,0,1]
	v_pk_fma_f32 v[10:11], v[124:125], v[48:49], v[10:11] op_sel_hi:[1,0,1]
	s_waitcnt lgkmcnt(0)
	v_pk_fma_f32 v[8:9], v[126:127], v[44:45], v[8:9] op_sel_hi:[1,0,1]
	v_pk_fma_f32 v[6:7], v[124:125], v[44:45], v[6:7] op_sel_hi:[1,0,1]
	v_add_u32_e32 v35, 44, v33
	ds_read2st64_b32 v[40:41], v35 offset1:32
	ds_read2st64_b32 v[42:43], v35 offset0:64 offset1:96
	ds_read_b32 v44, v33 offset:32812
	s_waitcnt lgkmcnt(2)
	v_mov_b32_e32 v46, v41
	s_waitcnt lgkmcnt(1)
	v_mov_b32_e32 v48, v43
	s_waitcnt vmcnt(4)
	v_pk_fma_f32 v[4:5], v[134:135], v[40:41], v[4:5] op_sel_hi:[1,0,1]
	v_pk_fma_f32 v[2:3], v[132:133], v[40:41], v[2:3] op_sel_hi:[1,0,1]
	v_pk_fma_f32 v[20:21], v[134:135], v[46:47], v[20:21] op_sel_hi:[1,0,1]
	v_pk_fma_f32 v[18:19], v[132:133], v[46:47], v[18:19] op_sel_hi:[1,0,1]
	v_pk_fma_f32 v[16:17], v[134:135], v[42:43], v[16:17] op_sel_hi:[1,0,1]
	v_pk_fma_f32 v[14:15], v[132:133], v[42:43], v[14:15] op_sel_hi:[1,0,1]
	v_pk_fma_f32 v[12:13], v[134:135], v[48:49], v[12:13] op_sel_hi:[1,0,1]
	v_pk_fma_f32 v[10:11], v[132:133], v[48:49], v[10:11] op_sel_hi:[1,0,1]
	s_waitcnt lgkmcnt(0)
	v_pk_fma_f32 v[8:9], v[134:135], v[44:45], v[8:9] op_sel_hi:[1,0,1]
	v_pk_fma_f32 v[6:7], v[132:133], v[44:45], v[6:7] op_sel_hi:[1,0,1]
	v_add_u32_e32 v35, 48, v33
	ds_read2st64_b32 v[40:41], v35 offset1:32
	ds_read2st64_b32 v[42:43], v35 offset0:64 offset1:96
	ds_read_b32 v44, v33 offset:32816
	s_waitcnt lgkmcnt(2)
	v_mov_b32_e32 v46, v41
	s_waitcnt lgkmcnt(1)
	v_mov_b32_e32 v48, v43
	s_waitcnt vmcnt(3)
; DI void p_mod(const Frame& F) {
;     ...
;         for (int k = kg * 128; k < kg * 128 + 128; ++k) { const f32x4 wv = __builtin_nontemporal_load((const f32x4*)(w + (size_t)k * 12288));
;             a0 += sv[k] * wv; a1 += sv[2048 + k] * wv; a2 += sv[4096 + k] * wv; a3 += sv[6144 + k] * wv; a4 += sv[8192 + k] * wv; }
	v_pk_fma_f32 v[4:5], v[138:139], v[40:41], v[4:5] op_sel_hi:[1,0,1]
	v_pk_fma_f32 v[2:3], v[136:137], v[40:41], v[2:3] op_sel_hi:[1,0,1]
	v_pk_fma_f32 v[20:21], v[138:139], v[46:47], v[20:21] op_sel_hi:[1,0,1]
	v_pk_fma_f32 v[18:19], v[136:137], v[46:47], v[18:19] op_sel_hi:[1,0,1]
	v_pk_fma_f32 v[16:17], v[138:139], v[42:43], v[16:17] op_sel_hi:[1,0,1]
	v_pk_fma_f32 v[14:15], v[136:137], v[42:43], v[14:15] op_sel_hi:[1,0,1]
	v_pk_fma_f32 v[12:13], v[138:139], v[48:49], v[12:13] op_sel_hi:[1,0,1]
	v_pk_fma_f32 v[10:11], v[136:137], v[48:49], v[10:11] op_sel_hi:[1,0,1]
	s_waitcnt lgkmcnt(0)
	v_pk_fma_f32 v[8:9], v[138:139], v[44:45], v[8:9] op_sel_hi:[1,0,1]
	v_pk_fma_f32 v[6:7], v[136:137], v[44:45], v[6:7] op_sel_hi:[1,0,1]
	v_add_u32_e32 v35, 52, v33
	ds_read2st64_b32 v[40:41], v35 offset1:32
	ds_read2st64_b32 v[42:43], v35 offset0:64 offset1:96
	ds_read_b32 v44, v33 offset:32820
	s_waitcnt lgkmcnt(2)
	v_mov_b32_e32 v46, v41
	s_waitcnt lgkmcnt(1)
	v_mov_b32_e32 v48, v43
	s_waitcnt vmcnt(2)
	v_pk_fma_f32 v[4:5], v[142:143], v[40:41], v[4:5] op_sel_hi:[1,0,1]
	v_pk_fma_f32 v[2:3], v[140:141], v[40:41], v[2:3] op_sel_hi:[1,0,1]
	v_pk_fma_f32 v[20:21], v[142:143], v[46:47], v[20:21] op_sel_hi:[1,0,1]
	v_pk_fma_f32 v[18:19], v[140:141], v[46:47], v[18:19] op_sel_hi:[1,0,1]
	v_pk_fma_f32 v[16:17], v[142:143], v[42:43], v[16:17] op_sel_hi:[1,0,1]
	v_pk_fma_f32 v[14:15], v[140:141], v[42:43], v[14:15] op_sel_hi:[1,0,1]
	v_pk_fma_f32 v[12:13], v[142:143], v[48:49], v[12:13] op_sel_hi:[1,0,1]
	v_pk_fma_f32 v[10:11], v[140:141], v[48:49], v[10:11] op_sel_hi:[1,0,1]
	s_waitcnt lgkmcnt(0)
	v_pk_fma_f32 v[8:9], v[142:143], v[44:45], v[8:9] op_sel_hi:[1,0,1]
	v_pk_fma_f32 v[6:7], v[140:141], v[44:45], v[6:7] op_sel_hi:[1,0,1]
	v_add_u32_e32 v35, 56, v33
	ds_read2st64_b32 v[40:41], v35 offset1:32
	ds_read2st64_b32 v[42:43], v35 offset0:64 offset1:96
	ds_read_b32 v44, v33 offset:32824
	s_waitcnt lgkmcnt(2)
	v_mov_b32_e32 v46, v41
	s_waitcnt lgkmcnt(1)
	v_mov_b32_e32 v48, v43
	s_waitcnt vmcnt(1)
	v_pk_fma_f32 v[4:5], v[146:147], v[40:41], v[4:5] op_sel_hi:[1,0,1]
	v_pk_fma_f32 v[2:3], v[144:145], v[40:41], v[2:3] op_sel_hi:[1,0,1]
	v_pk_fma_f32 v[20:21], v[146:147], v[46:47], v[20:21] op_sel_hi:[1,0,1]
	v_pk_fma_f32 v[18:19], v[144:145], v[46:47], v[18:19] op_sel_hi:[1,0,1]
	v_pk_fma_f32 v[16:17], v[146:147], v[42:43], v[16:17] op_sel_hi:[1,0,1]
	v_pk_fma_f32 v[14:15], v[144:145], v[42:43], v[14:15] op_sel_hi:[1,0,1]
	v_pk_fma_f32 v[12:13], v[146:147], v[48:49], v[12:13] op_sel_hi:[1,0,1]
	v_pk_fma_f32 v[10:11], v[144:145], v[48:49], v[10:11] op_sel_hi:[1,0,1]
	s_waitcnt lgkmcnt(0)
	v_pk_fma_f32 v[8:9], v[146:147], v[44:45], v[8:9] op_sel_hi:[1,0,1]
	v_pk_fma_f32 v[6:7], v[144:145], v[44:45], v[6:7] op_sel_hi:[1,0,1]
	v_add_u32_e32 v35, 60, v33
	ds_read2st64_b32 v[40:41], v35 offset1:32
	ds_read2st64_b32 v[42:43], v35 offset0:64 offset1:96
	ds_read_b32 v44, v33 offset:32828
	s_waitcnt lgkmcnt(2)
	v_mov_b32_e32 v46, v41
	s_waitcnt lgkmcnt(1)
	v_mov_b32_e32 v48, v43
	s_waitcnt vmcnt(0)
	v_pk_fma_f32 v[4:5], v[150:151], v[40:41], v[4:5] op_sel_hi:[1,0,1]
	v_pk_fma_f32 v[2:3], v[148:149], v[40:41], v[2:3] op_sel_hi:[1,0,1]
	v_pk_fma_f32 v[20:21], v[150:151], v[46:47], v[20:21] op_sel_hi:[1,0,1]
	v_pk_fma_f32 v[18:19], v[148:149], v[46:47], v[18:19] op_sel_hi:[1,0,1]
	v_pk_fma_f32 v[16:17], v[150:151], v[42:43], v[16:17] op_sel_hi:[1,0,1]
	v_pk_fma_f32 v[14:15], v[148:149], v[42:43], v[14:15] op_sel_hi:[1,0,1]
	v_pk_fma_f32 v[12:13], v[150:151], v[48:49], v[12:13] op_sel_hi:[1,0,1]
	v_pk_fma_f32 v[10:11], v[148:149], v[48:49], v[10:11] op_sel_hi:[1,0,1]
	s_waitcnt lgkmcnt(0)
	v_pk_fma_f32 v[8:9], v[150:151], v[44:45], v[8:9] op_sel_hi:[1,0,1]
	v_pk_fma_f32 v[6:7], v[148:149], v[44:45], v[6:7] op_sel_hi:[1,0,1]

;     DI const float* inp(int i) const { return as_global(P.in[i]); }
; DI void p_mod(const Frame& F) {
;     ...
;         const float* w = F.inp(4) + (size_t)l * 2048 * 12288 + colb + c4 * 4;
;         f32x4 a0 = {0.f, 0.f, 0.f, 0.f}, a1 = a0, a2 = a0, a3 = a0, a4 = a0;
; #pragma unroll 16
;         for (int k = kg * 128; k < kg * 128 + 128; ++k) { const f32x4 wv = __builtin_nontemporal_load((const f32x4*)(w + (size_t)k * 12288));
;             a0 += sv[k] * wv; a1 += sv[2048 + k] * wv; a2 += sv[4096 + k] * wv; a3 += sv[6144 + k] * wv; a4 += sv[8192 + k] * wv; }
.LBB0_105:
	s_waitcnt vmcnt(0)
	v_add_co_u32_e32 v152, vcc, s30, v30
	s_nop 1
	v_addc_co_u32_e32 v153, vcc, -1, v31, vcc
	s_mov_b64 s[12:13], 0xc000
	s_mov_b64 s[18:19], 0xc0000
	v_lshl_add_u64 v[154:155], v[152:153], 0, s[12:13]
	v_lshl_add_u64 v[156:157], v[154:155], 0, s[12:13]
	v_lshl_add_u64 v[158:159], v[156:157], 0, s[12:13]
	v_lshl_add_u64 v[160:161], v[158:159], 0, s[12:13]
	v_lshl_add_u64 v[162:163], v[160:161], 0, s[12:13]
	v_lshl_add_u64 v[164:165], v[162:163], 0, s[12:13]
	v_lshl_add_u64 v[166:167], v[164:165], 0, s[12:13]
	v_lshl_add_u64 v[168:169], v[166:167], 0, s[12:13]
	v_lshl_add_u64 v[170:171], v[168:169], 0, s[12:13]
	v_lshl_add_u64 v[172:173], v[170:171], 0, s[12:13]
	v_lshl_add_u64 v[174:175], v[172:173], 0, s[12:13]
	v_lshl_add_u64 v[176:177], v[174:175], 0, s[12:13]
	v_lshl_add_u64 v[178:179], v[176:177], 0, s[12:13]
	v_lshl_add_u64 v[180:181], v[178:179], 0, s[12:13]
	v_lshl_add_u64 v[182:183], v[180:181], 0, s[12:13]
	global_load_dwordx4 v[84:87], v[152:153], off nt
	global_load_dwordx4 v[88:91], v[154:155], off nt
	global_load_dwordx4 v[92:95], v[156:157], off nt
	global_load_dwordx4 v[96:99], v[158:159], off nt
	global_load_dwordx4 v[100:103], v[160:161], off nt
	global_load_dwordx4 v[104:107], v[162:163], off nt
	global_load_dwordx4 v[108:111], v[164:165], off nt
	global_load_dwordx4 v[112:115], v[166:167], off nt
	global_load_dwordx4 v[116:119], v[168:169], off nt
	global_load_dwordx4 v[120:123], v[170:171], off nt
	global_load_dwordx4 v[124:127], v[172:173], off nt
	global_load_dwordx4 v[132:135], v[174:175], off nt
	global_load_dwordx4 v[136:139], v[176:177], off nt
	global_load_dwordx4 v[140:143], v[178:179], off nt
	global_load_dwordx4 v[144:147], v[180:181], off nt
	global_load_dwordx4 v[148:151], v[182:183], off nt
	s_mov_b32 s8, 7
.Lpm2_loop:
	ds_read2st64_b32 v[42:43], v35 offset1:32
	ds_read2st64_b32 v[44:45], v35 offset0:64 offset1:96
	ds_read_b32 v46, v35 offset:32768
	s_waitcnt lgkmcnt(2)
	v_mov_b32_e32 v48, v43
	s_waitcnt lgkmcnt(1)
	v_mov_b32_e32 v50, v45
	s_waitcnt vmcnt(15)
	v_pk_fma_f32 v[4:5], v[86:87], v[42:43], v[4:5] op_sel_hi:[1,0,1]
	v_pk_fma_f32 v[2:3], v[84:85], v[42:43], v[2:3] op_sel_hi:[1,0,1]
	v_pk_fma_f32 v[20:21], v[86:87], v[48:49], v[20:21] op_sel_hi:[1,0,1]
	v_pk_fma_f32 v[18:19], v[84:85], v[48:49], v[18:19] op_sel_hi:[1,0,1]
	v_pk_fma_f32 v[16:17], v[86:87], v[44:45], v[16:17] op_sel_hi:[1,0,1]
	v_pk_fma_f32 v[14:15], v[84:85], v[44:45], v[14:15] op_sel_hi:[1,0,1]
	v_pk_fma_f32 v[12:13], v[86:87], v[50:51], v[12:13] op_sel_hi:[1,0,1]
	v_pk_fma_f32 v[10:11], v[84:85], v[50:51], v[10:11] op_sel_hi:[1,0,1]
	s_waitcnt lgkmcnt(0)
	v_pk_fma_f32 v[8:9], v[86:87], v[46:47], v[8:9] op_sel_hi:[1,0,1]
	v_pk_fma_f32 v[6:7], v[84:85], v[46:47], v[6:7] op_sel_hi:[1,0,1]
	v_lshl_add_u64 v[152:153], v[152:153], 0, s[18:19]
	global_load_dwordx4 v[84:87], v[152:153], off nt
	v_add_u32_e32 v37, 4, v35
	ds_read2st64_b32 v[42:43], v37 offset1:32
	ds_read2st64_b32 v[44:45], v37 offset0:64 offset1:96
	ds_read_b32 v46, v35 offset:32772
	s_waitcnt lgkmcnt(2)
	v_mov_b32_e32 v48, v43
	s_waitcnt lgkmcnt(1)
	v_mov_b32_e32 v50, v45
	s_waitcnt vmcnt(15)
	v_pk_fma_f32 v[4:5], v[90:91], v[42:43], v[4:5] op_sel_hi:[1,0,1]
	v_pk_fma_f32 v[2:3], v[88:89], v[42:43], v[2:3] op_sel_hi:[1,0,1]
	v_pk_fma_f32 v[20:21], v[90:91], v[48:49], v[20:21] op_sel_hi:[1,0,1]
	v_pk_fma_f32 v[18:19], v[88:89], v[48:49], v[18:19] op_sel_hi:[1,0,1]
	v_pk_fma_f32 v[16:17], v[90:91], v[44:45], v[16:17] op_sel_hi:[1,0,1]
	v_pk_fma_f32 v[14:15], v[88:89], v[44:45], v[14:15] op_sel_hi:[1,0,1]
	v_pk_fma_f32 v[12:13], v[90:91], v[50:51], v[12:13] op_sel_hi:[1,0,1]
	v_pk_fma_f32 v[10:11], v[88:89], v[50:51], v[10:11] op_sel_hi:[1,0,1]
	s_waitcnt lgkmcnt(0)
	v_pk_fma_f32 v[8:9], v[90:91], v[46:47], v[8:9] op_sel_hi:[1,0,1]
	v_pk_fma_f32 v[6:7], v[88:89], v[46:47], v[6:7] op_sel_hi:[1,0,1]
	v_lshl_add_u64 v[154:155], v[154:155], 0, s[18:19]
	global_load_dwordx4 v[88:91], v[154:155], off nt
	v_add_u32_e32 v37, 8, v35
	ds_read2st64_b32 v[42:43], v37 offset1:32
	ds_read2st64_b32 v[44:45], v37 offset0:64 offset1:96
	ds_read_b32 v46, v35 offset:32776
	s_waitcnt lgkmcnt(2)
	v_mov_b32_e32 v48, v43
	s_waitcnt lgkmcnt(1)
	v_mov_b32_e32 v50, v45
	s_waitcnt vmcnt(15)
	v_pk_fma_f32 v[4:5], v[94:95], v[42:43], v[4:5] op_sel_hi:[1,0,1]
	v_pk_fma_f32 v[2:3], v[92:93], v[42:43], v[2:3] op_sel_hi:[1,0,1]
	v_pk_fma_f32 v[20:21], v[94:95], v[48:49], v[20:21] op_sel_hi:[1,0,1]
	v_pk_fma_f32 v[18:19], v[92:93], v[48:49], v[18:19] op_sel_hi:[1,0,1]
	v_pk_fma_f32 v[16:17], v[94:95], v[44:45], v[16:17] op_sel_hi:[1,0,1]
	v_pk_fma_f32 v[14:15], v[92:93], v[44:45], v[14:15] op_sel_hi:[1,0,1]
	v_pk_fma_f32 v[12:13], v[94:95], v[50:51], v[12:13] op_sel_hi:[1,0,1]
	v_pk_fma_f32 v[10:11], v[92:93], v[50:51], v[10:11] op_sel_hi:[1,0,1]
	s_waitcnt lgkmcnt(0)
	v_pk_fma_f32 v[8:9], v[94:95], v[46:47], v[8:9] op_sel_hi:[1,0,1]
	v_pk_fma_f32 v[6:7], v[92:93], v[46:47], v[6:7] op_sel_hi:[1,0,1]
	v_lshl_add_u64 v[156:157], v[156:157], 0, s[18:19]
	global_load_dwordx4 v[92:95], v[156:157], off nt
	v_add_u32_e32 v37, 12, v35
	ds_read2st64_b32 v[42:43], v37 offset1:32
	ds_read2st64_b32 v[44:45], v37 offset0:64 offset1:96
	ds_read_b32 v46, v35 offset:32780
	s_waitcnt lgkmcnt(2)
	v_mov_b32_e32 v48, v43
	s_waitcnt lgkmcnt(1)
	v_mov_b32_e32 v50, v45
	s_waitcnt vmcnt(15)
	v_pk_fma_f32 v[4:5], v[98:99], v[42:43], v[4:5] op_sel_hi:[1,0,1]
	v_pk_fma_f32 v[2:3], v[96:97], v[42:43], v[2:3] op_sel_hi:[1,0,1]
	v_pk_fma_f32 v[20:21], v[98:99], v[48:49], v[20:21] op_sel_hi:[1,0,1]
	v_pk_fma_f32 v[18:19], v[96:97], v[48:49], v[18:19] op_sel_hi:[1,0,1]
	v_pk_fma_f32 v[16:17], v[98:99], v[44:45], v[16:17] op_sel_hi:[1,0,1]
	v_pk_fma_f32 v[14:15], v[96:97], v[44:45], v[14:15] op_sel_hi:[1,0,1]
	v_pk_fma_f32 v[12:13], v[98:99], v[50:51], v[12:13] op_sel_hi:[1,0,1]
	v_pk_fma_f32 v[10:11], v[96:97], v[50:51], v[10:11] op_sel_hi:[1,0,1]
	s_waitcnt lgkmcnt(0)
; DI void p_mod(const Frame& F) {
;     ...
;         for (int k = kg * 128; k < kg * 128 + 128; ++k) { const f32x4 wv = __builtin_nontemporal_load((const f32x4*)(w + (size_t)k * 12288));
;             a0 += sv[k] * wv; a1 += sv[2048 + k] * wv; a2 += sv[4096 + k] * wv; a3 += sv[6144 + k] * wv; a4 += sv[8192 + k] * wv; }
	v_pk_fma_f32 v[8:9], v[98:99], v[46:47], v[8:9] op_sel_hi:[1,0,1]
	v_pk_fma_f32 v[6:7], v[96:97], v[46:47], v[6:7] op_sel_hi:[1,0,1]
	v_lshl_add_u64 v[158:159], v[158:159], 0, s[18:19]
	global_load_dwordx4 v[96:99], v[158:159], off nt
	v_add_u32_e32 v37, 16, v35
	ds_read2st64_b32 v[42:43], v37 offset1:32
	ds_read2st64_b32 v[44:45], v37 offset0:64 offset1:96
	ds_read_b32 v46, v35 offset:32784
	s_waitcnt lgkmcnt(2)
	v_mov_b32_e32 v48, v43
	s_waitcnt lgkmcnt(1)
	v_mov_b32_e32 v50, v45
	s_waitcnt vmcnt(15)
	v_pk_fma_f32 v[4:5], v[102:103], v[42:43], v[4:5] op_sel_hi:[1,0,1]
	v_pk_fma_f32 v[2:3], v[100:101], v[42:43], v[2:3] op_sel_hi:[1,0,1]
	v_pk_fma_f32 v[20:21], v[102:103], v[48:49], v[20:21] op_sel_hi:[1,0,1]
	v_pk_fma_f32 v[18:19], v[100:101], v[48:49], v[18:19] op_sel_hi:[1,0,1]
	v_pk_fma_f32 v[16:17], v[102:103], v[44:45], v[16:17] op_sel_hi:[1,0,1]
	v_pk_fma_f32 v[14:15], v[100:101], v[44:45], v[14:15] op_sel_hi:[1,0,1]
	v_pk_fma_f32 v[12:13], v[102:103], v[50:51], v[12:13] op_sel_hi:[1,0,1]
	v_pk_fma_f32 v[10:11], v[100:101], v[50:51], v[10:11] op_sel_hi:[1,0,1]
	s_waitcnt lgkmcnt(0)
	v_pk_fma_f32 v[8:9], v[102:103], v[46:47], v[8:9] op_sel_hi:[1,0,1]
	v_pk_fma_f32 v[6:7], v[100:101], v[46:47], v[6:7] op_sel_hi:[1,0,1]
	v_lshl_add_u64 v[160:161], v[160:161], 0, s[18:19]
	global_load_dwordx4 v[100:103], v[160:161], off nt
	v_add_u32_e32 v37, 20, v35
	ds_read2st64_b32 v[42:43], v37 offset1:32
	ds_read2st64_b32 v[44:45], v37 offset0:64 offset1:96
	ds_read_b32 v46, v35 offset:32788
	s_waitcnt lgkmcnt(2)
	v_mov_b32_e32 v48, v43
	s_waitcnt lgkmcnt(1)
	v_mov_b32_e32 v50, v45
	s_waitcnt vmcnt(15)
	v_pk_fma_f32 v[4:5], v[106:107], v[42:43], v[4:5] op_sel_hi:[1,0,1]
	v_pk_fma_f32 v[2:3], v[104:105], v[42:43], v[2:3] op_sel_hi:[1,0,1]
	v_pk_fma_f32 v[20:21], v[106:107], v[48:49], v[20:21] op_sel_hi:[1,0,1]
	v_pk_fma_f32 v[18:19], v[104:105], v[48:49], v[18:19] op_sel_hi:[1,0,1]
	v_pk_fma_f32 v[16:17], v[106:107], v[44:45], v[16:17] op_sel_hi:[1,0,1]
	v_pk_fma_f32 v[14:15], v[104:105], v[44:45], v[14:15] op_sel_hi:[1,0,1]
	v_pk_fma_f32 v[12:13], v[106:107], v[50:51], v[12:13] op_sel_hi:[1,0,1]
	v_pk_fma_f32 v[10:11], v[104:105], v[50:51], v[10:11] op_sel_hi:[1,0,1]
	s_waitcnt lgkmcnt(0)
	v_pk_fma_f32 v[8:9], v[106:107], v[46:47], v[8:9] op_sel_hi:[1,0,1]
	v_pk_fma_f32 v[6:7], v[104:105], v[46:47], v[6:7] op_sel_hi:[1,0,1]
	v_lshl_add_u64 v[162:163], v[162:163], 0, s[18:19]
	global_load_dwordx4 v[104:107], v[162:163], off nt
	v_add_u32_e32 v37, 24, v35
	ds_read2st64_b32 v[42:43], v37 offset1:32
	ds_read2st64_b32 v[44:45], v37 offset0:64 offset1:96
	ds_read_b32 v46, v35 offset:32792
	s_waitcnt lgkmcnt(2)
	v_mov_b32_e32 v48, v43
	s_waitcnt lgkmcnt(1)
	v_mov_b32_e32 v50, v45
	s_waitcnt vmcnt(15)
	v_pk_fma_f32 v[4:5], v[110:111], v[42:43], v[4:5] op_sel_hi:[1,0,1]
	v_pk_fma_f32 v[2:3], v[108:109], v[42:43], v[2:3] op_sel_hi:[1,0,1]
	v_pk_fma_f32 v[20:21], v[110:111], v[48:49], v[20:21] op_sel_hi:[1,0,1]
	v_pk_fma_f32 v[18:19], v[108:109], v[48:49], v[18:19] op_sel_hi:[1,0,1]
	v_pk_fma_f32 v[16:17], v[110:111], v[44:45], v[16:17] op_sel_hi:[1,0,1]
	v_pk_fma_f32 v[14:15], v[108:109], v[44:45], v[14:15] op_sel_hi:[1,0,1]
	v_pk_fma_f32 v[12:13], v[110:111], v[50:51], v[12:13] op_sel_hi:[1,0,1]
	v_pk_fma_f32 v[10:11], v[108:109], v[50:51], v[10:11] op_sel_hi:[1,0,1]
	s_waitcnt lgkmcnt(0)
	v_pk_fma_f32 v[8:9], v[110:111], v[46:47], v[8:9] op_sel_hi:[1,0,1]
	v_pk_fma_f32 v[6:7], v[108:109], v[46:47], v[6:7] op_sel_hi:[1,0,1]
	v_lshl_add_u64 v[164:165], v[164:165], 0, s[18:19]
	global_load_dwordx4 v[108:111], v[164:165], off nt
	v_add_u32_e32 v37, 28, v35
	ds_read2st64_b32 v[42:43], v37 offset1:32
	ds_read2st64_b32 v[44:45], v37 offset0:64 offset1:96
	ds_read_b32 v46, v35 offset:32796
	s_waitcnt lgkmcnt(2)
	v_mov_b32_e32 v48, v43
	s_waitcnt lgkmcnt(1)
	v_mov_b32_e32 v50, v45
	s_waitcnt vmcnt(15)
	v_pk_fma_f32 v[4:5], v[114:115], v[42:43], v[4:5] op_sel_hi:[1,0,1]
	v_pk_fma_f32 v[2:3], v[112:113], v[42:43], v[2:3] op_sel_hi:[1,0,1]
	v_pk_fma_f32 v[20:21], v[114:115], v[48:49], v[20:21] op_sel_hi:[1,0,1]
	v_pk_fma_f32 v[18:19], v[112:113], v[48:49], v[18:19] op_sel_hi:[1,0,1]
	v_pk_fma_f32 v[16:17], v[114:115], v[44:45], v[16:17] op_sel_hi:[1,0,1]
	v_pk_fma_f32 v[14:15], v[112:113], v[44:45], v[14:15] op_sel_hi:[1,0,1]
	v_pk_fma_f32 v[12:13], v[114:115], v[50:51], v[12:13] op_sel_hi:[1,0,1]
	v_pk_fma_f32 v[10:11], v[112:113], v[50:51], v[10:11] op_sel_hi:[1,0,1]
	s_waitcnt lgkmcnt(0)
	v_pk_fma_f32 v[8:9], v[114:115], v[46:47], v[8:9] op_sel_hi:[1,0,1]
	v_pk_fma_f32 v[6:7], v[112:113], v[46:47], v[6:7] op_sel_hi:[1,0,1]
	v_lshl_add_u64 v[166:167], v[166:167], 0, s[18:19]
	global_load_dwordx4 v[112:115], v[166:167], off nt
	v_add_u32_e32 v37, 32, v35
	ds_read2st64_b32 v[42:43], v37 offset1:32
	ds_read2st64_b32 v[44:45], v37 offset0:64 offset1:96
	ds_read_b32 v46, v35 offset:32800
	s_waitcnt lgkmcnt(2)
	v_mov_b32_e32 v48, v43
	s_waitcnt lgkmcnt(1)
	v_mov_b32_e32 v50, v45
	s_waitcnt vmcnt(15)
	v_pk_fma_f32 v[4:5], v[118:119], v[42:43], v[4:5] op_sel_hi:[1,0,1]
	v_pk_fma_f32 v[2:3], v[116:117], v[42:43], v[2:3] op_sel_hi:[1,0,1]
	v_pk_fma_f32 v[20:21], v[118:119], v[48:49], v[20:21] op_sel_hi:[1,0,1]
	v_pk_fma_f32 v[18:19], v[116:117], v[48:49], v[18:19] op_sel_hi:[1,0,1]
	v_pk_fma_f32 v[16:17], v[118:119], v[44:45], v[16:17] op_sel_hi:[1,0,1]
	v_pk_fma_f32 v[14:15], v[116:117], v[44:45], v[14:15] op_sel_hi:[1,0,1]
	v_pk_fma_f32 v[12:13], v[118:119], v[50:51], v[12:13] op_sel_hi:[1,0,1]
	v_pk_fma_f32 v[10:11], v[116:117], v[50:51], v[10:11] op_sel_hi:[1,0,1]
	s_waitcnt lgkmcnt(0)
; DI void p_mod(const Frame& F) {
;     ...
;         for (int k = kg * 128; k < kg * 128 + 128; ++k) { const f32x4 wv = __builtin_nontemporal_load((const f32x4*)(w + (size_t)k * 12288));
;             a0 += sv[k] * wv; a1 += sv[2048 + k] * wv; a2 += sv[4096 + k] * wv; a3 += sv[6144 + k] * wv; a4 += sv[8192 + k] * wv; }
	v_pk_fma_f32 v[8:9], v[118:119], v[46:47], v[8:9] op_sel_hi:[1,0,1]
	v_pk_fma_f32 v[6:7], v[116:117], v[46:47], v[6:7] op_sel_hi:[1,0,1]
	v_lshl_add_u64 v[168:169], v[168:169], 0, s[18:19]
	global_load_dwordx4 v[116:119], v[168:169], off nt
	v_add_u32_e32 v37, 36, v35
	ds_read2st64_b32 v[42:43], v37 offset1:32
	ds_read2st64_b32 v[44:45], v37 offset0:64 offset1:96
	ds_read_b32 v46, v35 offset:32804
	s_waitcnt lgkmcnt(2)
	v_mov_b32_e32 v48, v43
	s_waitcnt lgkmcnt(1)
	v_mov_b32_e32 v50, v45
	s_waitcnt vmcnt(15)
	v_pk_fma_f32 v[4:5], v[122:123], v[42:43], v[4:5] op_sel_hi:[1,0,1]
	v_pk_fma_f32 v[2:3], v[120:121], v[42:43], v[2:3] op_sel_hi:[1,0,1]
	v_pk_fma_f32 v[20:21], v[122:123], v[48:49], v[20:21] op_sel_hi:[1,0,1]
	v_pk_fma_f32 v[18:19], v[120:121], v[48:49], v[18:19] op_sel_hi:[1,0,1]
	v_pk_fma_f32 v[16:17], v[122:123], v[44:45], v[16:17] op_sel_hi:[1,0,1]
	v_pk_fma_f32 v[14:15], v[120:121], v[44:45], v[14:15] op_sel_hi:[1,0,1]
	v_pk_fma_f32 v[12:13], v[122:123], v[50:51], v[12:13] op_sel_hi:[1,0,1]
	v_pk_fma_f32 v[10:11], v[120:121], v[50:51], v[10:11] op_sel_hi:[1,0,1]
	s_waitcnt lgkmcnt(0)
	v_pk_fma_f32 v[8:9], v[122:123], v[46:47], v[8:9] op_sel_hi:[1,0,1]
	v_pk_fma_f32 v[6:7], v[120:121], v[46:47], v[6:7] op_sel_hi:[1,0,1]
	v_lshl_add_u64 v[170:171], v[170:171], 0, s[18:19]
	global_load_dwordx4 v[120:123], v[170:171], off nt
	v_add_u32_e32 v37, 40, v35
	ds_read2st64_b32 v[42:43], v37 offset1:32
	ds_read2st64_b32 v[44:45], v37 offset0:64 offset1:96
	ds_read_b32 v46, v35 offset:32808
	s_waitcnt lgkmcnt(2)
	v_mov_b32_e32 v48, v43
	s_waitcnt lgkmcnt(1)
	v_mov_b32_e32 v50, v45
	s_waitcnt vmcnt(15)
	v_pk_fma_f32 v[4:5], v[126:127], v[42:43], v[4:5] op_sel_hi:[1,0,1]
	v_pk_fma_f32 v[2:3], v[124:125], v[42:43], v[2:3] op_sel_hi:[1,0,1]
	v_pk_fma_f32 v[20:21], v[126:127], v[48:49], v[20:21] op_sel_hi:[1,0,1]
	v_pk_fma_f32 v[18:19], v[124:125], v[48:49], v[18:19] op_sel_hi:[1,0,1]
	v_pk_fma_f32 v[16:17], v[126:127], v[44:45], v[16:17] op_sel_hi:[1,0,1]
	v_pk_fma_f32 v[14:15], v[124:125], v[44:45], v[14:15] op_sel_hi:[1,0,1]
	v_pk_fma_f32 v[12:13], v[126:127], v[50:51], v[12:13] op_sel_hi:[1,0,1]
	v_pk_fma_f32 v[10:11], v[124:125], v[50:51], v[10:11] op_sel_hi:[1,0,1]
	s_waitcnt lgkmcnt(0)
	v_pk_fma_f32 v[8:9], v[126:127], v[46:47], v[8:9] op_sel_hi:[1,0,1]
	v_pk_fma_f32 v[6:7], v[124:125], v[46:47], v[6:7] op_sel_hi:[1,0,1]
	v_lshl_add_u64 v[172:173], v[172:173], 0, s[18:19]
	global_load_dwordx4 v[124:127], v[172:173], off nt
	v_add_u32_e32 v37, 44, v35
	ds_read2st64_b32 v[42:43], v37 offset1:32
	ds_read2st64_b32 v[44:45], v37 offset0:64 offset1:96
	ds_read_b32 v46, v35 offset:32812
	s_waitcnt lgkmcnt(2)
	v_mov_b32_e32 v48, v43
	s_waitcnt lgkmcnt(1)
	v_mov_b32_e32 v50, v45
	s_waitcnt vmcnt(15)
	v_pk_fma_f32 v[4:5], v[134:135], v[42:43], v[4:5] op_sel_hi:[1,0,1]
	v_pk_fma_f32 v[2:3], v[132:133], v[42:43], v[2:3] op_sel_hi:[1,0,1]
	v_pk_fma_f32 v[20:21], v[134:135], v[48:49], v[20:21] op_sel_hi:[1,0,1]
	v_pk_fma_f32 v[18:19], v[132:133], v[48:49], v[18:19] op_sel_hi:[1,0,1]
	v_pk_fma_f32 v[16:17], v[134:135], v[44:45], v[16:17] op_sel_hi:[1,0,1]
	v_pk_fma_f32 v[14:15], v[132:133], v[44:45], v[14:15] op_sel_hi:[1,0,1]
	v_pk_fma_f32 v[12:13], v[134:135], v[50:51], v[12:13] op_sel_hi:[1,0,1]
	v_pk_fma_f32 v[10:11], v[132:133], v[50:51], v[10:11] op_sel_hi:[1,0,1]
	s_waitcnt lgkmcnt(0)
	v_pk_fma_f32 v[8:9], v[134:135], v[46:47], v[8:9] op_sel_hi:[1,0,1]
	v_pk_fma_f32 v[6:7], v[132:133], v[46:47], v[6:7] op_sel_hi:[1,0,1]
	v_lshl_add_u64 v[174:175], v[174:175], 0, s[18:19]
	global_load_dwordx4 v[132:135], v[174:175], off nt
	v_add_u32_e32 v37, 48, v35
	ds_read2st64_b32 v[42:43], v37 offset1:32
	ds_read2st64_b32 v[44:45], v37 offset0:64 offset1:96
	ds_read_b32 v46, v35 offset:32816
	s_waitcnt lgkmcnt(2)
	v_mov_b32_e32 v48, v43
	s_waitcnt lgkmcnt(1)
	v_mov_b32_e32 v50, v45
	s_waitcnt vmcnt(15)
	v_pk_fma_f32 v[4:5], v[138:139], v[42:43], v[4:5] op_sel_hi:[1,0,1]
	v_pk_fma_f32 v[2:3], v[136:137], v[42:43], v[2:3] op_sel_hi:[1,0,1]
	v_pk_fma_f32 v[20:21], v[138:139], v[48:49], v[20:21] op_sel_hi:[1,0,1]
	v_pk_fma_f32 v[18:19], v[136:137], v[48:49], v[18:19] op_sel_hi:[1,0,1]
	v_pk_fma_f32 v[16:17], v[138:139], v[44:45], v[16:17] op_sel_hi:[1,0,1]
	v_pk_fma_f32 v[14:15], v[136:137], v[44:45], v[14:15] op_sel_hi:[1,0,1]
	v_pk_fma_f32 v[12:13], v[138:139], v[50:51], v[12:13] op_sel_hi:[1,0,1]
	v_pk_fma_f32 v[10:11], v[136:137], v[50:51], v[10:11] op_sel_hi:[1,0,1]
	s_waitcnt lgkmcnt(0)
	v_pk_fma_f32 v[8:9], v[138:139], v[46:47], v[8:9] op_sel_hi:[1,0,1]
	v_pk_fma_f32 v[6:7], v[136:137], v[46:47], v[6:7] op_sel_hi:[1,0,1]
	v_lshl_add_u64 v[176:177], v[176:177], 0, s[18:19]
	global_load_dwordx4 v[136:139], v[176:177], off nt
	v_add_u32_e32 v37, 52, v35
	ds_read2st64_b32 v[42:43], v37 offset1:32
	ds_read2st64_b32 v[44:45], v37 offset0:64 offset1:96
	ds_read_b32 v46, v35 offset:32820
	s_waitcnt lgkmcnt(2)
	v_mov_b32_e32 v48, v43
	s_waitcnt lgkmcnt(1)
	v_mov_b32_e32 v50, v45
	s_waitcnt vmcnt(15)
	v_pk_fma_f32 v[4:5], v[142:143], v[42:43], v[4:5] op_sel_hi:[1,0,1]
	v_pk_fma_f32 v[2:3], v[140:141], v[42:43], v[2:3] op_sel_hi:[1,0,1]
	v_pk_fma_f32 v[20:21], v[142:143], v[48:49], v[20:21] op_sel_hi:[1,0,1]
	v_pk_fma_f32 v[18:19], v[140:141], v[48:49], v[18:19] op_sel_hi:[1,0,1]
	v_pk_fma_f32 v[16:17], v[142:143], v[44:45], v[16:17] op_sel_hi:[1,0,1]
	v_pk_fma_f32 v[14:15], v[140:141], v[44:45], v[14:15] op_sel_hi:[1,0,1]
	v_pk_fma_f32 v[12:13], v[142:143], v[50:51], v[12:13] op_sel_hi:[1,0,1]
	v_pk_fma_f32 v[10:11], v[140:141], v[50:51], v[10:11] op_sel_hi:[1,0,1]
	s_waitcnt lgkmcnt(0)
; DI void p_mod(const Frame& F) {
;     ...
;         for (int k = kg * 128; k < kg * 128 + 128; ++k) { const f32x4 wv = __builtin_nontemporal_load((const f32x4*)(w + (size_t)k * 12288));
;             a0 += sv[k] * wv; a1 += sv[2048 + k] * wv; a2 += sv[4096 + k] * wv; a3 += sv[6144 + k] * wv; a4 += sv[8192 + k] * wv; }
	v_pk_fma_f32 v[8:9], v[142:143], v[46:47], v[8:9] op_sel_hi:[1,0,1]
	v_pk_fma_f32 v[6:7], v[140:141], v[46:47], v[6:7] op_sel_hi:[1,0,1]
	v_lshl_add_u64 v[178:179], v[178:179], 0, s[18:19]
	global_load_dwordx4 v[140:143], v[178:179], off nt
	v_add_u32_e32 v37, 56, v35
	ds_read2st64_b32 v[42:43], v37 offset1:32
	ds_read2st64_b32 v[44:45], v37 offset0:64 offset1:96
	ds_read_b32 v46, v35 offset:32824
	s_waitcnt lgkmcnt(2)
	v_mov_b32_e32 v48, v43
	s_waitcnt lgkmcnt(1)
	v_mov_b32_e32 v50, v45
	s_waitcnt vmcnt(15)
	v_pk_fma_f32 v[4:5], v[146:147], v[42:43], v[4:5] op_sel_hi:[1,0,1]
	v_pk_fma_f32 v[2:3], v[144:145], v[42:43], v[2:3] op_sel_hi:[1,0,1]
	v_pk_fma_f32 v[20:21], v[146:147], v[48:49], v[20:21] op_sel_hi:[1,0,1]
	v_pk_fma_f32 v[18:19], v[144:145], v[48:49], v[18:19] op_sel_hi:[1,0,1]
	v_pk_fma_f32 v[16:17], v[146:147], v[44:45], v[16:17] op_sel_hi:[1,0,1]
	v_pk_fma_f32 v[14:15], v[144:145], v[44:45], v[14:15] op_sel_hi:[1,0,1]
	v_pk_fma_f32 v[12:13], v[146:147], v[50:51], v[12:13] op_sel_hi:[1,0,1]
	v_pk_fma_f32 v[10:11], v[144:145], v[50:51], v[10:11] op_sel_hi:[1,0,1]
	s_waitcnt lgkmcnt(0)
	v_pk_fma_f32 v[8:9], v[146:147], v[46:47], v[8:9] op_sel_hi:[1,0,1]
	v_pk_fma_f32 v[6:7], v[144:145], v[46:47], v[6:7] op_sel_hi:[1,0,1]
	v_lshl_add_u64 v[180:181], v[180:181], 0, s[18:19]
	global_load_dwordx4 v[144:147], v[180:181], off nt
	v_add_u32_e32 v37, 60, v35
	ds_read2st64_b32 v[42:43], v37 offset1:32
	ds_read2st64_b32 v[44:45], v37 offset0:64 offset1:96
	ds_read_b32 v46, v35 offset:32828
	s_waitcnt lgkmcnt(2)
	v_mov_b32_e32 v48, v43
	s_waitcnt lgkmcnt(1)
	v_mov_b32_e32 v50, v45
	s_waitcnt vmcnt(15)
	v_pk_fma_f32 v[4:5], v[150:151], v[42:43], v[4:5] op_sel_hi:[1,0,1]
	v_pk_fma_f32 v[2:3], v[148:149], v[42:43], v[2:3] op_sel_hi:[1,0,1]
	v_pk_fma_f32 v[20:21], v[150:151], v[48:49], v[20:21] op_sel_hi:[1,0,1]
	v_pk_fma_f32 v[18:19], v[148:149], v[48:49], v[18:19] op_sel_hi:[1,0,1]
	v_pk_fma_f32 v[16:17], v[150:151], v[44:45], v[16:17] op_sel_hi:[1,0,1]
	v_pk_fma_f32 v[14:15], v[148:149], v[44:45], v[14:15] op_sel_hi:[1,0,1]
	v_pk_fma_f32 v[12:13], v[150:151], v[50:51], v[12:13] op_sel_hi:[1,0,1]
	v_pk_fma_f32 v[10:11], v[148:149], v[50:51], v[10:11] op_sel_hi:[1,0,1]
	s_waitcnt lgkmcnt(0)
	v_pk_fma_f32 v[8:9], v[150:151], v[46:47], v[8:9] op_sel_hi:[1,0,1]
	v_pk_fma_f32 v[6:7], v[148:149], v[46:47], v[6:7] op_sel_hi:[1,0,1]
	v_lshl_add_u64 v[182:183], v[182:183], 0, s[18:19]
	global_load_dwordx4 v[148:151], v[182:183], off nt
	v_add_u32_e32 v35, 64, v35
	s_add_i32 s8, s8, -1
	s_cmp_lg_u32 s8, 0
	s_cbranch_scc1 .Lpm2_loop
	ds_read2st64_b32 v[42:43], v35 offset1:32
	ds_read2st64_b32 v[44:45], v35 offset0:64 offset1:96
	ds_read_b32 v46, v35 offset:32768
	s_waitcnt lgkmcnt(2)
	v_mov_b32_e32 v48, v43
	s_waitcnt lgkmcnt(1)
	v_mov_b32_e32 v50, v45
	s_waitcnt vmcnt(15)
	v_pk_fma_f32 v[4:5], v[86:87], v[42:43], v[4:5] op_sel_hi:[1,0,1]
	v_pk_fma_f32 v[2:3], v[84:85], v[42:43], v[2:3] op_sel_hi:[1,0,1]
	v_pk_fma_f32 v[20:21], v[86:87], v[48:49], v[20:21] op_sel_hi:[1,0,1]
	v_pk_fma_f32 v[18:19], v[84:85], v[48:49], v[18:19] op_sel_hi:[1,0,1]
	v_pk_fma_f32 v[16:17], v[86:87], v[44:45], v[16:17] op_sel_hi:[1,0,1]
	v_pk_fma_f32 v[14:15], v[84:85], v[44:45], v[14:15] op_sel_hi:[1,0,1]
	v_pk_fma_f32 v[12:13], v[86:87], v[50:51], v[12:13] op_sel_hi:[1,0,1]
	v_pk_fma_f32 v[10:11], v[84:85], v[50:51], v[10:11] op_sel_hi:[1,0,1]
	s_waitcnt lgkmcnt(0)
	v_pk_fma_f32 v[8:9], v[86:87], v[46:47], v[8:9] op_sel_hi:[1,0,1]
	v_pk_fma_f32 v[6:7], v[84:85], v[46:47], v[6:7] op_sel_hi:[1,0,1]
	v_add_u32_e32 v37, 4, v35
	ds_read2st64_b32 v[42:43], v37 offset1:32
	ds_read2st64_b32 v[44:45], v37 offset0:64 offset1:96
	ds_read_b32 v46, v35 offset:32772
	s_waitcnt lgkmcnt(2)
	v_mov_b32_e32 v48, v43
	s_waitcnt lgkmcnt(1)
	v_mov_b32_e32 v50, v45
	s_waitcnt vmcnt(14)
	v_pk_fma_f32 v[4:5], v[90:91], v[42:43], v[4:5] op_sel_hi:[1,0,1]
	v_pk_fma_f32 v[2:3], v[88:89], v[42:43], v[2:3] op_sel_hi:[1,0,1]
	v_pk_fma_f32 v[20:21], v[90:91], v[48:49], v[20:21] op_sel_hi:[1,0,1]
	v_pk_fma_f32 v[18:19], v[88:89], v[48:49], v[18:19] op_sel_hi:[1,0,1]
	v_pk_fma_f32 v[16:17], v[90:91], v[44:45], v[16:17] op_sel_hi:[1,0,1]
	v_pk_fma_f32 v[14:15], v[88:89], v[44:45], v[14:15] op_sel_hi:[1,0,1]
	v_pk_fma_f32 v[12:13], v[90:91], v[50:51], v[12:13] op_sel_hi:[1,0,1]
	v_pk_fma_f32 v[10:11], v[88:89], v[50:51], v[10:11] op_sel_hi:[1,0,1]
	s_waitcnt lgkmcnt(0)
	v_pk_fma_f32 v[8:9], v[90:91], v[46:47], v[8:9] op_sel_hi:[1,0,1]
	v_pk_fma_f32 v[6:7], v[88:89], v[46:47], v[6:7] op_sel_hi:[1,0,1]
	v_add_u32_e32 v37, 8, v35
	ds_read2st64_b32 v[42:43], v37 offset1:32
	ds_read2st64_b32 v[44:45], v37 offset0:64 offset1:96
	ds_read_b32 v46, v35 offset:32776
	s_waitcnt lgkmcnt(2)
	v_mov_b32_e32 v48, v43
	s_waitcnt lgkmcnt(1)
	v_mov_b32_e32 v50, v45
	s_waitcnt vmcnt(13)
	v_pk_fma_f32 v[4:5], v[94:95], v[42:43], v[4:5] op_sel_hi:[1,0,1]
	v_pk_fma_f32 v[2:3], v[92:93], v[42:43], v[2:3] op_sel_hi:[1,0,1]
	v_pk_fma_f32 v[20:21], v[94:95], v[48:49], v[20:21] op_sel_hi:[1,0,1]
	v_pk_fma_f32 v[18:19], v[92:93], v[48:49], v[18:19] op_sel_hi:[1,0,1]
	v_pk_fma_f32 v[16:17], v[94:95], v[44:45], v[16:17] op_sel_hi:[1,0,1]
	v_pk_fma_f32 v[14:15], v[92:93], v[44:45], v[14:15] op_sel_hi:[1,0,1]
	v_pk_fma_f32 v[12:13], v[94:95], v[50:51], v[12:13] op_sel_hi:[1,0,1]
	v_pk_fma_f32 v[10:11], v[92:93], v[50:51], v[10:11] op_sel_hi:[1,0,1]
	s_waitcnt lgkmcnt(0)
	v_pk_fma_f32 v[8:9], v[94:95], v[46:47], v[8:9] op_sel_hi:[1,0,1]
	v_pk_fma_f32 v[6:7], v[92:93], v[46:47], v[6:7] op_sel_hi:[1,0,1]
	v_add_u32_e32 v37, 12, v35
	ds_read2st64_b32 v[42:43], v37 offset1:32
	ds_read2st64_b32 v[44:45], v37 offset0:64 offset1:96
	ds_read_b32 v46, v35 offset:32780
	s_waitcnt lgkmcnt(2)
; DI void p_mod(const Frame& F) {
;     ...
;         for (int k = kg * 128; k < kg * 128 + 128; ++k) { const f32x4 wv = __builtin_nontemporal_load((const f32x4*)(w + (size_t)k * 12288));
;             a0 += sv[k] * wv; a1 += sv[2048 + k] * wv; a2 += sv[4096 + k] * wv; a3 += sv[6144 + k] * wv; a4 += sv[8192 + k] * wv; }
	v_mov_b32_e32 v48, v43
	s_waitcnt lgkmcnt(1)
	v_mov_b32_e32 v50, v45
	s_waitcnt vmcnt(12)
	v_pk_fma_f32 v[4:5], v[98:99], v[42:43], v[4:5] op_sel_hi:[1,0,1]
	v_pk_fma_f32 v[2:3], v[96:97], v[42:43], v[2:3] op_sel_hi:[1,0,1]
	v_pk_fma_f32 v[20:21], v[98:99], v[48:49], v[20:21] op_sel_hi:[1,0,1]
	v_pk_fma_f32 v[18:19], v[96:97], v[48:49], v[18:19] op_sel_hi:[1,0,1]
	v_pk_fma_f32 v[16:17], v[98:99], v[44:45], v[16:17] op_sel_hi:[1,0,1]
	v_pk_fma_f32 v[14:15], v[96:97], v[44:45], v[14:15] op_sel_hi:[1,0,1]
	v_pk_fma_f32 v[12:13], v[98:99], v[50:51], v[12:13] op_sel_hi:[1,0,1]
	v_pk_fma_f32 v[10:11], v[96:97], v[50:51], v[10:11] op_sel_hi:[1,0,1]
	s_waitcnt lgkmcnt(0)
	v_pk_fma_f32 v[8:9], v[98:99], v[46:47], v[8:9] op_sel_hi:[1,0,1]
	v_pk_fma_f32 v[6:7], v[96:97], v[46:47], v[6:7] op_sel_hi:[1,0,1]
	v_add_u32_e32 v37, 16, v35
	ds_read2st64_b32 v[42:43], v37 offset1:32
	ds_read2st64_b32 v[44:45], v37 offset0:64 offset1:96
	ds_read_b32 v46, v35 offset:32784
	s_waitcnt lgkmcnt(2)
	v_mov_b32_e32 v48, v43
	s_waitcnt lgkmcnt(1)
	v_mov_b32_e32 v50, v45
	s_waitcnt vmcnt(11)
	v_pk_fma_f32 v[4:5], v[102:103], v[42:43], v[4:5] op_sel_hi:[1,0,1]
	v_pk_fma_f32 v[2:3], v[100:101], v[42:43], v[2:3] op_sel_hi:[1,0,1]
	v_pk_fma_f32 v[20:21], v[102:103], v[48:49], v[20:21] op_sel_hi:[1,0,1]
	v_pk_fma_f32 v[18:19], v[100:101], v[48:49], v[18:19] op_sel_hi:[1,0,1]
	v_pk_fma_f32 v[16:17], v[102:103], v[44:45], v[16:17] op_sel_hi:[1,0,1]
	v_pk_fma_f32 v[14:15], v[100:101], v[44:45], v[14:15] op_sel_hi:[1,0,1]
	v_pk_fma_f32 v[12:13], v[102:103], v[50:51], v[12:13] op_sel_hi:[1,0,1]
	v_pk_fma_f32 v[10:11], v[100:101], v[50:51], v[10:11] op_sel_hi:[1,0,1]
	s_waitcnt lgkmcnt(0)
	v_pk_fma_f32 v[8:9], v[102:103], v[46:47], v[8:9] op_sel_hi:[1,0,1]
	v_pk_fma_f32 v[6:7], v[100:101], v[46:47], v[6:7] op_sel_hi:[1,0,1]
	v_add_u32_e32 v37, 20, v35
	ds_read2st64_b32 v[42:43], v37 offset1:32
	ds_read2st64_b32 v[44:45], v37 offset0:64 offset1:96
	ds_read_b32 v46, v35 offset:32788
	s_waitcnt lgkmcnt(2)
	v_mov_b32_e32 v48, v43
	s_waitcnt lgkmcnt(1)
	v_mov_b32_e32 v50, v45
	s_waitcnt vmcnt(10)
	v_pk_fma_f32 v[4:5], v[106:107], v[42:43], v[4:5] op_sel_hi:[1,0,1]
	v_pk_fma_f32 v[2:3], v[104:105], v[42:43], v[2:3] op_sel_hi:[1,0,1]
	v_pk_fma_f32 v[20:21], v[106:107], v[48:49], v[20:21] op_sel_hi:[1,0,1]
	v_pk_fma_f32 v[18:19], v[104:105], v[48:49], v[18:19] op_sel_hi:[1,0,1]
	v_pk_fma_f32 v[16:17], v[106:107], v[44:45], v[16:17] op_sel_hi:[1,0,1]
	v_pk_fma_f32 v[14:15], v[104:105], v[44:45], v[14:15] op_sel_hi:[1,0,1]
	v_pk_fma_f32 v[12:13], v[106:107], v[50:51], v[12:13] op_sel_hi:[1,0,1]
	v_pk_fma_f32 v[10:11], v[104:105], v[50:51], v[10:11] op_sel_hi:[1,0,1]
	s_waitcnt lgkmcnt(0)
	v_pk_fma_f32 v[8:9], v[106:107], v[46:47], v[8:9] op_sel_hi:[1,0,1]
	v_pk_fma_f32 v[6:7], v[104:105], v[46:47], v[6:7] op_sel_hi:[1,0,1]
	v_add_u32_e32 v37, 24, v35
	ds_read2st64_b32 v[42:43], v37 offset1:32
	ds_read2st64_b32 v[44:45], v37 offset0:64 offset1:96
	ds_read_b32 v46, v35 offset:32792
	s_waitcnt lgkmcnt(2)
	v_mov_b32_e32 v48, v43
	s_waitcnt lgkmcnt(1)
	v_mov_b32_e32 v50, v45
	s_waitcnt vmcnt(9)
	v_pk_fma_f32 v[4:5], v[110:111], v[42:43], v[4:5] op_sel_hi:[1,0,1]
	v_pk_fma_f32 v[2:3], v[108:109], v[42:43], v[2:3] op_sel_hi:[1,0,1]
	v_pk_fma_f32 v[20:21], v[110:111], v[48:49], v[20:21] op_sel_hi:[1,0,1]
	v_pk_fma_f32 v[18:19], v[108:109], v[48:49], v[18:19] op_sel_hi:[1,0,1]
	v_pk_fma_f32 v[16:17], v[110:111], v[44:45], v[16:17] op_sel_hi:[1,0,1]
	v_pk_fma_f32 v[14:15], v[108:109], v[44:45], v[14:15] op_sel_hi:[1,0,1]
	v_pk_fma_f32 v[12:13], v[110:111], v[50:51], v[12:13] op_sel_hi:[1,0,1]
	v_pk_fma_f32 v[10:11], v[108:109], v[50:51], v[10:11] op_sel_hi:[1,0,1]
	s_waitcnt lgkmcnt(0)
	v_pk_fma_f32 v[8:9], v[110:111], v[46:47], v[8:9] op_sel_hi:[1,0,1]
	v_pk_fma_f32 v[6:7], v[108:109], v[46:47], v[6:7] op_sel_hi:[1,0,1]
	v_add_u32_e32 v37, 28, v35
	ds_read2st64_b32 v[42:43], v37 offset1:32
	ds_read2st64_b32 v[44:45], v37 offset0:64 offset1:96
	ds_read_b32 v46, v35 offset:32796
	s_waitcnt lgkmcnt(2)
	v_mov_b32_e32 v48, v43
	s_waitcnt lgkmcnt(1)
	v_mov_b32_e32 v50, v45
	s_waitcnt vmcnt(8)
	v_pk_fma_f32 v[4:5], v[114:115], v[42:43], v[4:5] op_sel_hi:[1,0,1]
	v_pk_fma_f32 v[2:3], v[112:113], v[42:43], v[2:3] op_sel_hi:[1,0,1]
	v_pk_fma_f32 v[20:21], v[114:115], v[48:49], v[20:21] op_sel_hi:[1,0,1]
	v_pk_fma_f32 v[18:19], v[112:113], v[48:49], v[18:19] op_sel_hi:[1,0,1]
	v_pk_fma_f32 v[16:17], v[114:115], v[44:45], v[16:17] op_sel_hi:[1,0,1]
	v_pk_fma_f32 v[14:15], v[112:113], v[44:45], v[14:15] op_sel_hi:[1,0,1]
	v_pk_fma_f32 v[12:13], v[114:115], v[50:51], v[12:13] op_sel_hi:[1,0,1]
	v_pk_fma_f32 v[10:11], v[112:113], v[50:51], v[10:11] op_sel_hi:[1,0,1]
	s_waitcnt lgkmcnt(0)
	v_pk_fma_f32 v[8:9], v[114:115], v[46:47], v[8:9] op_sel_hi:[1,0,1]
	v_pk_fma_f32 v[6:7], v[112:113], v[46:47], v[6:7] op_sel_hi:[1,0,1]
	v_add_u32_e32 v37, 32, v35
	ds_read2st64_b32 v[42:43], v37 offset1:32
	ds_read2st64_b32 v[44:45], v37 offset0:64 offset1:96
	ds_read_b32 v46, v35 offset:32800
	s_waitcnt lgkmcnt(2)
	v_mov_b32_e32 v48, v43
	s_waitcnt lgkmcnt(1)
	v_mov_b32_e32 v50, v45
	s_waitcnt vmcnt(7)
	v_pk_fma_f32 v[4:5], v[118:119], v[42:43], v[4:5] op_sel_hi:[1,0,1]
	v_pk_fma_f32 v[2:3], v[116:117], v[42:43], v[2:3] op_sel_hi:[1,0,1]
	v_pk_fma_f32 v[20:21], v[118:119], v[48:49], v[20:21] op_sel_hi:[1,0,1]
	v_pk_fma_f32 v[18:19], v[116:117], v[48:49], v[18:19] op_sel_hi:[1,0,1]
	v_pk_fma_f32 v[16:17], v[118:119], v[44:45], v[16:17] op_sel_hi:[1,0,1]
	v_pk_fma_f32 v[14:15], v[116:117], v[44:45], v[14:15] op_sel_hi:[1,0,1]
	v_pk_fma_f32 v[12:13], v[118:119], v[50:51], v[12:13] op_sel_hi:[1,0,1]
	v_pk_fma_f32 v[10:11], v[116:117], v[50:51], v[10:11] op_sel_hi:[1,0,1]
	s_waitcnt lgkmcnt(0)
; DI void p_mod(const Frame& F) {
;     ...
;         for (int k = kg * 128; k < kg * 128 + 128; ++k) { const f32x4 wv = __builtin_nontemporal_load((const f32x4*)(w + (size_t)k * 12288));
;             a0 += sv[k] * wv; a1 += sv[2048 + k] * wv; a2 += sv[4096 + k] * wv; a3 += sv[6144 + k] * wv; a4 += sv[8192 + k] * wv; }
	v_pk_fma_f32 v[8:9], v[118:119], v[46:47], v[8:9] op_sel_hi:[1,0,1]
	v_pk_fma_f32 v[6:7], v[116:117], v[46:47], v[6:7] op_sel_hi:[1,0,1]
	v_add_u32_e32 v37, 36, v35
	ds_read2st64_b32 v[42:43], v37 offset1:32
	ds_read2st64_b32 v[44:45], v37 offset0:64 offset1:96
	ds_read_b32 v46, v35 offset:32804
	s_waitcnt lgkmcnt(2)
	v_mov_b32_e32 v48, v43
	s_waitcnt lgkmcnt(1)
	v_mov_b32_e32 v50, v45
	s_waitcnt vmcnt(6)
	v_pk_fma_f32 v[4:5], v[122:123], v[42:43], v[4:5] op_sel_hi:[1,0,1]
	v_pk_fma_f32 v[2:3], v[120:121], v[42:43], v[2:3] op_sel_hi:[1,0,1]
	v_pk_fma_f32 v[20:21], v[122:123], v[48:49], v[20:21] op_sel_hi:[1,0,1]
	v_pk_fma_f32 v[18:19], v[120:121], v[48:49], v[18:19] op_sel_hi:[1,0,1]
	v_pk_fma_f32 v[16:17], v[122:123], v[44:45], v[16:17] op_sel_hi:[1,0,1]
	v_pk_fma_f32 v[14:15], v[120:121], v[44:45], v[14:15] op_sel_hi:[1,0,1]
	v_pk_fma_f32 v[12:13], v[122:123], v[50:51], v[12:13] op_sel_hi:[1,0,1]
	v_pk_fma_f32 v[10:11], v[120:121], v[50:51], v[10:11] op_sel_hi:[1,0,1]
	s_waitcnt lgkmcnt(0)
	v_pk_fma_f32 v[8:9], v[122:123], v[46:47], v[8:9] op_sel_hi:[1,0,1]
	v_pk_fma_f32 v[6:7], v[120:121], v[46:47], v[6:7] op_sel_hi:[1,0,1]
	v_add_u32_e32 v37, 40, v35
	ds_read2st64_b32 v[42:43], v37 offset1:32
	ds_read2st64_b32 v[44:45], v37 offset0:64 offset1:96
	ds_read_b32 v46, v35 offset:32808
	s_waitcnt lgkmcnt(2)
	v_mov_b32_e32 v48, v43
	s_waitcnt lgkmcnt(1)
	v_mov_b32_e32 v50, v45
	s_waitcnt vmcnt(5)
	v_pk_fma_f32 v[4:5], v[126:127], v[42:43], v[4:5] op_sel_hi:[1,0,1]
	v_pk_fma_f32 v[2:3], v[124:125], v[42:43], v[2:3] op_sel_hi:[1,0,1]
	v_pk_fma_f32 v[20:21], v[126:127], v[48:49], v[20:21] op_sel_hi:[1,0,1]
	v_pk_fma_f32 v[18:19], v[124:125], v[48:49], v[18:19] op_sel_hi:[1,0,1]
	v_pk_fma_f32 v[16:17], v[126:127], v[44:45], v[16:17] op_sel_hi:[1,0,1]
	v_pk_fma_f32 v[14:15], v[124:125], v[44:45], v[14:15] op_sel_hi:[1,0,1]
	v_pk_fma_f32 v[12:13], v[126:127], v[50:51], v[12:13] op_sel_hi:[1,0,1]
	v_pk_fma_f32 v[10:11], v[124:125], v[50:51], v[10:11] op_sel_hi:[1,0,1]
	s_waitcnt lgkmcnt(0)
	v_pk_fma_f32 v[8:9], v[126:127], v[46:47], v[8:9] op_sel_hi:[1,0,1]
	v_pk_fma_f32 v[6:7], v[124:125], v[46:47], v[6:7] op_sel_hi:[1,0,1]
	v_add_u32_e32 v37, 44, v35
	ds_read2st64_b32 v[42:43], v37 offset1:32
	ds_read2st64_b32 v[44:45], v37 offset0:64 offset1:96
	ds_read_b32 v46, v35 offset:32812
	s_waitcnt lgkmcnt(2)
	v_mov_b32_e32 v48, v43
	s_waitcnt lgkmcnt(1)
	v_mov_b32_e32 v50, v45
	s_waitcnt vmcnt(4)
	v_pk_fma_f32 v[4:5], v[134:135], v[42:43], v[4:5] op_sel_hi:[1,0,1]
	v_pk_fma_f32 v[2:3], v[132:133], v[42:43], v[2:3] op_sel_hi:[1,0,1]
	v_pk_fma_f32 v[20:21], v[134:135], v[48:49], v[20:21] op_sel_hi:[1,0,1]
	v_pk_fma_f32 v[18:19], v[132:133], v[48:49], v[18:19] op_sel_hi:[1,0,1]
	v_pk_fma_f32 v[16:17], v[134:135], v[44:45], v[16:17] op_sel_hi:[1,0,1]
	v_pk_fma_f32 v[14:15], v[132:133], v[44:45], v[14:15] op_sel_hi:[1,0,1]
	v_pk_fma_f32 v[12:13], v[134:135], v[50:51], v[12:13] op_sel_hi:[1,0,1]
	v_pk_fma_f32 v[10:11], v[132:133], v[50:51], v[10:11] op_sel_hi:[1,0,1]
	s_waitcnt lgkmcnt(0)
	v_pk_fma_f32 v[8:9], v[134:135], v[46:47], v[8:9] op_sel_hi:[1,0,1]
	v_pk_fma_f32 v[6:7], v[132:133], v[46:47], v[6:7] op_sel_hi:[1,0,1]
	v_add_u32_e32 v37, 48, v35
	ds_read2st64_b32 v[42:43], v37 offset1:32
	ds_read2st64_b32 v[44:45], v37 offset0:64 offset1:96
	ds_read_b32 v46, v35 offset:32816
	s_waitcnt lgkmcnt(2)
	v_mov_b32_e32 v48, v43
	s_waitcnt lgkmcnt(1)
	v_mov_b32_e32 v50, v45
	s_waitcnt vmcnt(3)
; DI void p_mod(const Frame& F) {
;     ...
;         for (int k = kg * 128; k < kg * 128 + 128; ++k) { const f32x4 wv = __builtin_nontemporal_load((const f32x4*)(w + (size_t)k * 12288));
;             a0 += sv[k] * wv; a1 += sv[2048 + k] * wv; a2 += sv[4096 + k] * wv; a3 += sv[6144 + k] * wv; a4 += sv[8192 + k] * wv; }
	v_pk_fma_f32 v[4:5], v[138:139], v[42:43], v[4:5] op_sel_hi:[1,0,1]
	v_pk_fma_f32 v[2:3], v[136:137], v[42:43], v[2:3] op_sel_hi:[1,0,1]
	v_pk_fma_f32 v[20:21], v[138:139], v[48:49], v[20:21] op_sel_hi:[1,0,1]
	v_pk_fma_f32 v[18:19], v[136:137], v[48:49], v[18:19] op_sel_hi:[1,0,1]
	v_pk_fma_f32 v[16:17], v[138:139], v[44:45], v[16:17] op_sel_hi:[1,0,1]
	v_pk_fma_f32 v[14:15], v[136:137], v[44:45], v[14:15] op_sel_hi:[1,0,1]
	v_pk_fma_f32 v[12:13], v[138:139], v[50:51], v[12:13] op_sel_hi:[1,0,1]
	v_pk_fma_f32 v[10:11], v[136:137], v[50:51], v[10:11] op_sel_hi:[1,0,1]
	s_waitcnt lgkmcnt(0)
	v_pk_fma_f32 v[8:9], v[138:139], v[46:47], v[8:9] op_sel_hi:[1,0,1]
	v_pk_fma_f32 v[6:7], v[136:137], v[46:47], v[6:7] op_sel_hi:[1,0,1]
	v_add_u32_e32 v37, 52, v35
	ds_read2st64_b32 v[42:43], v37 offset1:32
	ds_read2st64_b32 v[44:45], v37 offset0:64 offset1:96
	ds_read_b32 v46, v35 offset:32820
	s_waitcnt lgkmcnt(2)
	v_mov_b32_e32 v48, v43
	s_waitcnt lgkmcnt(1)
	v_mov_b32_e32 v50, v45
	s_waitcnt vmcnt(2)
	v_pk_fma_f32 v[4:5], v[142:143], v[42:43], v[4:5] op_sel_hi:[1,0,1]
	v_pk_fma_f32 v[2:3], v[140:141], v[42:43], v[2:3] op_sel_hi:[1,0,1]
	v_pk_fma_f32 v[20:21], v[142:143], v[48:49], v[20:21] op_sel_hi:[1,0,1]
	v_pk_fma_f32 v[18:19], v[140:141], v[48:49], v[18:19] op_sel_hi:[1,0,1]
	v_pk_fma_f32 v[16:17], v[142:143], v[44:45], v[16:17] op_sel_hi:[1,0,1]
	v_pk_fma_f32 v[14:15], v[140:141], v[44:45], v[14:15] op_sel_hi:[1,0,1]
	v_pk_fma_f32 v[12:13], v[142:143], v[50:51], v[12:13] op_sel_hi:[1,0,1]
	v_pk_fma_f32 v[10:11], v[140:141], v[50:51], v[10:11] op_sel_hi:[1,0,1]
	s_waitcnt lgkmcnt(0)
	v_pk_fma_f32 v[8:9], v[142:143], v[46:47], v[8:9] op_sel_hi:[1,0,1]
	v_pk_fma_f32 v[6:7], v[140:141], v[46:47], v[6:7] op_sel_hi:[1,0,1]
	v_add_u32_e32 v37, 56, v35
	ds_read2st64_b32 v[42:43], v37 offset1:32
	ds_read2st64_b32 v[44:45], v37 offset0:64 offset1:96
	ds_read_b32 v46, v35 offset:32824
	s_waitcnt lgkmcnt(2)
	v_mov_b32_e32 v48, v43
	s_waitcnt lgkmcnt(1)
	v_mov_b32_e32 v50, v45
	s_waitcnt vmcnt(1)
	v_pk_fma_f32 v[4:5], v[146:147], v[42:43], v[4:5] op_sel_hi:[1,0,1]
	v_pk_fma_f32 v[2:3], v[144:145], v[42:43], v[2:3] op_sel_hi:[1,0,1]
	v_pk_fma_f32 v[20:21], v[146:147], v[48:49], v[20:21] op_sel_hi:[1,0,1]
	v_pk_fma_f32 v[18:19], v[144:145], v[48:49], v[18:19] op_sel_hi:[1,0,1]
	v_pk_fma_f32 v[16:17], v[146:147], v[44:45], v[16:17] op_sel_hi:[1,0,1]
	v_pk_fma_f32 v[14:15], v[144:145], v[44:45], v[14:15] op_sel_hi:[1,0,1]
	v_pk_fma_f32 v[12:13], v[146:147], v[50:51], v[12:13] op_sel_hi:[1,0,1]
	v_pk_fma_f32 v[10:11], v[144:145], v[50:51], v[10:11] op_sel_hi:[1,0,1]
	s_waitcnt lgkmcnt(0)
	v_pk_fma_f32 v[8:9], v[146:147], v[46:47], v[8:9] op_sel_hi:[1,0,1]
	v_pk_fma_f32 v[6:7], v[144:145], v[46:47], v[6:7] op_sel_hi:[1,0,1]
	v_add_u32_e32 v37, 60, v35
	ds_read2st64_b32 v[42:43], v37 offset1:32
	ds_read2st64_b32 v[44:45], v37 offset0:64 offset1:96
	ds_read_b32 v46, v35 offset:32828
	s_waitcnt lgkmcnt(2)
	v_mov_b32_e32 v48, v43
	s_waitcnt lgkmcnt(1)
	v_mov_b32_e32 v50, v45
	s_waitcnt vmcnt(0)
	v_pk_fma_f32 v[4:5], v[150:151], v[42:43], v[4:5] op_sel_hi:[1,0,1]
	v_pk_fma_f32 v[2:3], v[148:149], v[42:43], v[2:3] op_sel_hi:[1,0,1]
	v_pk_fma_f32 v[20:21], v[150:151], v[48:49], v[20:21] op_sel_hi:[1,0,1]
	v_pk_fma_f32 v[18:19], v[148:149], v[48:49], v[18:19] op_sel_hi:[1,0,1]
	v_pk_fma_f32 v[16:17], v[150:151], v[44:45], v[16:17] op_sel_hi:[1,0,1]
	v_pk_fma_f32 v[14:15], v[148:149], v[44:45], v[14:15] op_sel_hi:[1,0,1]
	v_pk_fma_f32 v[12:13], v[150:151], v[50:51], v[12:13] op_sel_hi:[1,0,1]
	v_pk_fma_f32 v[10:11], v[148:149], v[50:51], v[10:11] op_sel_hi:[1,0,1]
	s_waitcnt lgkmcnt(0)
	v_pk_fma_f32 v[8:9], v[150:151], v[46:47], v[8:9] op_sel_hi:[1,0,1]
	v_pk_fma_f32 v[6:7], v[148:149], v[46:47], v[6:7] op_sel_hi:[1,0,1]
